# hyena filter section rewritten (H2 table stored chunk-interleaved for coalesced row loads, transposed weight copy in LDS, packed f32 FMAs, 3-deep load ring); MoE combine phase rewritten with batched l
# speedup vs baseline: 1.0776x; 1.0142x over previous
; #define layer launder_s(layer_)
; __device__ __forceinline__ void h2_item(const Params& p, int item, unsigned char* smem) {
;     ...
;   h1s[tl * 64 + j] = sinf(fr * pre);
;   __syncthreads();
;   const float* w2 = p.in[26] + (size_t)layer * 64 * 64;
;   float pre2 = p.in[27][layer * 64 + j];
;   for (int i = 0; i < 64; i++) pre2 += h1s[tl * 64 + i] * w2[i * 64 + j];
;   float* H2 = (float*)(p.ws + O_H2);
;   H2[((size_t)layer * 2304 + tt) * 64 + j] = sinf(fr * pre2);
.LBB0_78:
	s_andn2_saveexec_b64 s[4:5], s[36:37]
	v_mul_f32_e64 v2, |v0|, s51
	v_rndne_f32_e32 v7, v2
	v_cvt_i32_f32_e32 v2, v7
	v_fma_f32 v3, v7, s52, |v0|
	v_fmac_f32_e32 v3, 0xb3a22168, v7
	v_fmac_f32_e32 v3, 0xa7c234c4, v7
	s_or_b64 exec, exec, s[4:5]
	v_mul_f32_e32 v7, v3, v3
	v_fmamk_f32 v9, v7, 0xb94c1982, v18
	v_fmaak_f32 v9, v7, v9, 0xbe2aaa9d
	v_mul_f32_e32 v9, v7, v9
	v_fmac_f32_e32 v3, v3, v9
	v_fmamk_f32 v9, v7, 0x37d75334, v19
	v_fmaak_f32 v9, v7, v9, 0x3d2aabf7
	v_fmaak_f32 v9, v7, v9, 0xbf000004
	v_fma_f32 v7, v7, v9, 1.0
	v_and_b32_e32 v9, 1, v2
	v_lshlrev_b32_e32 v2, 30, v2
	v_cmp_eq_u32_e32 vcc, 0, v9
	v_and_b32_e32 v2, 0x80000000, v2
	v_xor_b32_e32 v1, v1, v0
	v_cndmask_b32_e32 v3, v7, v3, vcc
	v_xor_b32_e32 v1, v1, v2
	s_and_b64 s[4:5], s[34:35], exec
	v_xor_b32_e32 v1, v1, v3
	v_cmp_class_f32_e64 vcc, v0, s54
	s_cselect_b32 s12, 0x900, 0
	v_ashrrev_i32_e32 v9, 31, v8
	v_cndmask_b32_e32 v2, v26, v1, vcc
	v_lshrrev_b32_e32 v0, 4, v8
	v_lshlrev_b32_e32 v0, 12, v0
	v_and_b32_e32 v1, 15, v8
	v_lshl_or_b32 v0, v1, 4, v0
	v_lshrrev_b32_e32 v1, 4, v4
	v_lshl_or_b32 v0, v1, 8, v0
	v_and_b32_e32 v1, 12, v4
	v_or_b32_e32 v0, v0, v1
	v_lshl_add_u32 v1, v8, 8, v4
	v_cmp_gt_u32_e32 vcc, 0x800, v8
	v_mov_b32_e32 v3, s12
	s_nop 0
	v_cndmask_b32_e32 v0, v1, v0, vcc
	v_lshl_add_u32 v0, v3, 8, v0
	v_mov_b32_e32 v1, 0
	v_lshl_add_u64 v[0:1], v[12:13], 0, v[0:1]
	v_add_co_u32_e32 v0, vcc, 0x6c6c000, v0
	s_nop 1
	v_addc_co_u32_e32 v1, vcc, 0, v1, vcc
	global_store_dword v[0:1], v2, off
	s_waitcnt lgkmcnt(0)
	s_barrier

; #define layer launder_s(layer_)
; __device__ __forceinline__ void hyena_task(const Params& p, int layer, int c, bool isctx, unsigned char* smem) {
;     ...
;       const float* w3 = p.in[28] + (size_t)layer * 64 * 2048;
;       if (tid < 256) { int k = tid & 63, q = tid >> 6; misc[q * 64 + k] = w3[k * 2048 + (q >> 1) * 1024 + (q & 1) * 512 + c]; }
;       __syncthreads();
.LBB0_343:
	s_xor_b64 s[40:41], s[50:51], -1
	s_and_b64 vcc, exec, s[40:41]
	s_barrier
	s_cbranch_vccnz .LBB0_357
	s_mov_b64 s[4:5], exec
	v_readlane_b32 s6, v255, 27
	v_readlane_b32 s7, v255, 28
	s_and_b64 s[6:7], s[4:5], s[6:7]
	s_mov_b64 exec, s[6:7]
	s_cbranch_execz .LBB0_346
	v_mov_b64_e32 v[0:1], s[28:29]
	global_load_dwordx2 v[0:1], v[0:1], off offset:224
	v_readlane_b32 s6, v255, 29
	v_readlane_b32 s7, v255, 30
	s_waitcnt vmcnt(0) lgkmcnt(0)
	s_nop 0
	v_lshl_add_u64 v[0:1], v[0:1], 0, s[6:7]
	v_lshl_add_u64 v[0:1], v[70:71], 2, v[0:1]
	global_load_dword v0, v[0:1], off
	s_waitcnt vmcnt(0) lgkmcnt(0)
	ds_write_b32 v109, v0
	v_and_b32_e32 v1, 63, v66
	v_lshrrev_b32_e32 v2, 6, v66
	v_lshlrev_b32_e32 v1, 4, v1
	v_lshl_add_u32 v1, v2, 2, v1
	ds_write_b32 v1, v0 offset:49408

; __device__ __forceinline__ void hyena_task(const Params& p, int layer, int c, bool isctx, unsigned char* smem) {
;     ...
;       float ssq0 = 0.f, ssq1 = 0.f;
; #pragma unroll 2
;       for (int t = tid; t < Ls; t += NT) {
;         const float4* hp = (const float4*)(H2 + (size_t)t * 64);
;         float a0 = 0.f, a1 = 0.f, a2 = 0.f, a3 = 0.f;
; #pragma unroll
;         for (int q = 0; q < 16; q++) {
;           float4 hh = hp[q];
;           a0 += hh.x * misc[4 * q] + hh.y * misc[4 * q + 1] + hh.z * misc[4 * q + 2] + hh.w * misc[4 * q + 3];
;           a1 += hh.x * misc[64 + 4 * q] + hh.y * misc[64 + 4 * q + 1] + hh.z * misc[64 + 4 * q + 2] + hh.w * misc[64 + 4 * q + 3];
;           a2 += hh.x * misc[128 + 4 * q] + hh.y * misc[128 + 4 * q + 1] + hh.z * misc[128 + 4 * q + 2] + hh.w * misc[128 + 4 * q + 3];
;           a3 += hh.x * misc[192 + 4 * q] + hh.y * misc[192 + 4 * q + 1] + hh.z * misc[192 + 4 * q + 2] + hh.w * misc[192 + 4 * q + 3];
;         }
.LBB0_349:
	s_or_b64 exec, exec, s[6:7]
	v_lshrrev_b32_e32 v96, 4, v66
	v_lshlrev_b32_e32 v96, 12, v96
	v_and_b32_e32 v97, 15, v66
	v_lshl_or_b32 v96, v97, 4, v96
	v_mov_b32_e32 v97, 0
	v_lshl_add_u64 v[92:93], v[74:75], 0, v[96:97]
	s_mov_b64 s[4:5], 0x6c6c000
	v_lshl_add_u64 v[92:93], v[92:93], 0, s[4:5]
	s_mov_b64 s[4:5], 0x20000
	v_mov_b32_e32 v94, 0xc100
	v_lshlrev_b32_e32 v98, 2, v66
	v_add_u32_e32 v99, 0x20700, v98
	v_mov_b32_e32 v64, 0
	v_mov_b32_e32 v65, 0
	v_mov_b32_e32 v52, 0
	v_mov_b32_e32 v53, 0
	v_mov_b32_e32 v54, 0
	v_mov_b32_e32 v55, 0
	global_load_dwordx4 v[162:165], v[92:93], off
	global_load_dwordx4 v[166:169], v[92:93], off offset:256
	global_load_dwordx4 v[170:173], v[92:93], off offset:512
	global_load_dwordx4 v[174:177], v[92:93], off offset:768
	global_load_dwordx4 v[178:181], v[92:93], off offset:1024
	global_load_dwordx4 v[182:185], v[92:93], off offset:1280
	global_load_dwordx4 v[186:189], v[92:93], off offset:1536
	global_load_dwordx4 v[190:193], v[92:93], off offset:1792
	global_load_dwordx4 v[0:3], v[92:93], off offset:2048
	global_load_dwordx4 v[4:7], v[92:93], off offset:2304
	global_load_dwordx4 v[8:11], v[92:93], off offset:2560
	global_load_dwordx4 v[12:15], v[92:93], off offset:2816
	global_load_dwordx4 v[16:19], v[92:93], off offset:3072
	global_load_dwordx4 v[20:23], v[92:93], off offset:3328
	global_load_dwordx4 v[24:27], v[92:93], off offset:3584
	global_load_dwordx4 v[28:31], v[92:93], off offset:3840
	v_lshl_add_u64 v[92:93], v[92:93], 0, s[4:5]
	ds_read_b128 v[136:139], v94
	ds_read_b128 v[140:143], v94 offset:16
	ds_read_b128 v[144:147], v94 offset:32
	ds_read_b128 v[148:151], v94 offset:48
	global_load_dwordx4 v[194:197], v[92:93], off
	global_load_dwordx4 v[198:201], v[92:93], off offset:256
	global_load_dwordx4 v[202:205], v[92:93], off offset:512
	global_load_dwordx4 v[206:209], v[92:93], off offset:768
	global_load_dwordx4 v[210:213], v[92:93], off offset:1024
	global_load_dwordx4 v[32:35], v[92:93], off offset:1280
	global_load_dwordx4 v[36:39], v[92:93], off offset:1536
	global_load_dwordx4 v[40:43], v[92:93], off offset:1792
	s_waitcnt vmcnt(16)
	ds_read_b128 v[44:47], v94 offset:64
	ds_read_b128 v[48:51], v94 offset:80
	ds_read_b128 v[152:155], v94 offset:96
	ds_read_b128 v[156:159], v94 offset:112
	s_waitcnt lgkmcnt(4)
	v_pk_fma_f32 v[52:53], v[162:163], v[136:137], v[52:53] op_sel_hi:[0,1,1]
	v_pk_fma_f32 v[54:55], v[162:163], v[138:139], v[54:55] op_sel_hi:[0,1,1]
	v_pk_fma_f32 v[52:53], v[162:163], v[140:141], v[52:53] op_sel:[1,0,0]
	v_pk_fma_f32 v[54:55], v[162:163], v[142:143], v[54:55] op_sel:[1,0,0]
	v_pk_fma_f32 v[52:53], v[164:165], v[144:145], v[52:53] op_sel_hi:[0,1,1]
	v_pk_fma_f32 v[54:55], v[164:165], v[146:147], v[54:55] op_sel_hi:[0,1,1]
	v_pk_fma_f32 v[52:53], v[164:165], v[148:149], v[52:53] op_sel:[1,0,0]
	v_pk_fma_f32 v[54:55], v[164:165], v[150:151], v[54:55] op_sel:[1,0,0]
	ds_read_b128 v[136:139], v94 offset:128
	ds_read_b128 v[140:143], v94 offset:144
	ds_read_b128 v[144:147], v94 offset:160
	ds_read_b128 v[148:151], v94 offset:176
	s_waitcnt lgkmcnt(4)
	v_pk_fma_f32 v[52:53], v[166:167], v[44:45], v[52:53] op_sel_hi:[0,1,1]
	v_pk_fma_f32 v[54:55], v[166:167], v[46:47], v[54:55] op_sel_hi:[0,1,1]
	v_pk_fma_f32 v[52:53], v[166:167], v[48:49], v[52:53] op_sel:[1,0,0]
	v_pk_fma_f32 v[54:55], v[166:167], v[50:51], v[54:55] op_sel:[1,0,0]
	v_pk_fma_f32 v[52:53], v[168:169], v[152:153], v[52:53] op_sel_hi:[0,1,1]
	v_pk_fma_f32 v[54:55], v[168:169], v[154:155], v[54:55] op_sel_hi:[0,1,1]
	v_pk_fma_f32 v[52:53], v[168:169], v[156:157], v[52:53] op_sel:[1,0,0]
	v_pk_fma_f32 v[54:55], v[168:169], v[158:159], v[54:55] op_sel:[1,0,0]
	ds_read_b128 v[44:47], v94 offset:192
	ds_read_b128 v[48:51], v94 offset:208
	ds_read_b128 v[152:155], v94 offset:224
	ds_read_b128 v[156:159], v94 offset:240
	s_waitcnt lgkmcnt(4)
	v_pk_fma_f32 v[52:53], v[170:171], v[136:137], v[52:53] op_sel_hi:[0,1,1]
	v_pk_fma_f32 v[54:55], v[170:171], v[138:139], v[54:55] op_sel_hi:[0,1,1]
	v_pk_fma_f32 v[52:53], v[170:171], v[140:141], v[52:53] op_sel:[1,0,0]
	v_pk_fma_f32 v[54:55], v[170:171], v[142:143], v[54:55] op_sel:[1,0,0]
	v_pk_fma_f32 v[52:53], v[172:173], v[144:145], v[52:53] op_sel_hi:[0,1,1]
	v_pk_fma_f32 v[54:55], v[172:173], v[146:147], v[54:55] op_sel_hi:[0,1,1]
	v_pk_fma_f32 v[52:53], v[172:173], v[148:149], v[52:53] op_sel:[1,0,0]
	v_pk_fma_f32 v[54:55], v[172:173], v[150:151], v[54:55] op_sel:[1,0,0]
	ds_read_b128 v[136:139], v94 offset:256
	ds_read_b128 v[140:143], v94 offset:272
	ds_read_b128 v[144:147], v94 offset:288
	ds_read_b128 v[148:151], v94 offset:304
	s_waitcnt lgkmcnt(4)
	v_pk_fma_f32 v[52:53], v[174:175], v[44:45], v[52:53] op_sel_hi:[0,1,1]
	v_pk_fma_f32 v[54:55], v[174:175], v[46:47], v[54:55] op_sel_hi:[0,1,1]
	v_pk_fma_f32 v[52:53], v[174:175], v[48:49], v[52:53] op_sel:[1,0,0]
	v_pk_fma_f32 v[54:55], v[174:175], v[50:51], v[54:55] op_sel:[1,0,0]
	v_pk_fma_f32 v[52:53], v[176:177], v[152:153], v[52:53] op_sel_hi:[0,1,1]
	v_pk_fma_f32 v[54:55], v[176:177], v[154:155], v[54:55] op_sel_hi:[0,1,1]
	v_pk_fma_f32 v[52:53], v[176:177], v[156:157], v[52:53] op_sel:[1,0,0]
	v_pk_fma_f32 v[54:55], v[176:177], v[158:159], v[54:55] op_sel:[1,0,0]
	ds_read_b128 v[44:47], v94 offset:320
	ds_read_b128 v[48:51], v94 offset:336
	ds_read_b128 v[152:155], v94 offset:352
	ds_read_b128 v[156:159], v94 offset:368
	s_waitcnt lgkmcnt(4)
; __device__ __forceinline__ void hyena_task(const Params& p, int layer, int c, bool isctx, unsigned char* smem) {
;     ...
;         for (int q = 0; q < 16; q++) {
;           float4 hh = hp[q];
;           a0 += hh.x * misc[4 * q] + hh.y * misc[4 * q + 1] + hh.z * misc[4 * q + 2] + hh.w * misc[4 * q + 3];
;           a1 += hh.x * misc[64 + 4 * q] + hh.y * misc[64 + 4 * q + 1] + hh.z * misc[64 + 4 * q + 2] + hh.w * misc[64 + 4 * q + 3];
;           a2 += hh.x * misc[128 + 4 * q] + hh.y * misc[128 + 4 * q + 1] + hh.z * misc[128 + 4 * q + 2] + hh.w * misc[128 + 4 * q + 3];
;           a3 += hh.x * misc[192 + 4 * q] + hh.y * misc[192 + 4 * q + 1] + hh.z * misc[192 + 4 * q + 2] + hh.w * misc[192 + 4 * q + 3];
;         }
	v_pk_fma_f32 v[52:53], v[178:179], v[136:137], v[52:53] op_sel_hi:[0,1,1]
	v_pk_fma_f32 v[54:55], v[178:179], v[138:139], v[54:55] op_sel_hi:[0,1,1]
	v_pk_fma_f32 v[52:53], v[178:179], v[140:141], v[52:53] op_sel:[1,0,0]
	v_pk_fma_f32 v[54:55], v[178:179], v[142:143], v[54:55] op_sel:[1,0,0]
	v_pk_fma_f32 v[52:53], v[180:181], v[144:145], v[52:53] op_sel_hi:[0,1,1]
	v_pk_fma_f32 v[54:55], v[180:181], v[146:147], v[54:55] op_sel_hi:[0,1,1]
	v_pk_fma_f32 v[52:53], v[180:181], v[148:149], v[52:53] op_sel:[1,0,0]
	v_pk_fma_f32 v[54:55], v[180:181], v[150:151], v[54:55] op_sel:[1,0,0]
	ds_read_b128 v[136:139], v94 offset:384
	ds_read_b128 v[140:143], v94 offset:400
	ds_read_b128 v[144:147], v94 offset:416
	ds_read_b128 v[148:151], v94 offset:432
	s_waitcnt lgkmcnt(4)
	v_pk_fma_f32 v[52:53], v[182:183], v[44:45], v[52:53] op_sel_hi:[0,1,1]
	v_pk_fma_f32 v[54:55], v[182:183], v[46:47], v[54:55] op_sel_hi:[0,1,1]
	v_pk_fma_f32 v[52:53], v[182:183], v[48:49], v[52:53] op_sel:[1,0,0]
	v_pk_fma_f32 v[54:55], v[182:183], v[50:51], v[54:55] op_sel:[1,0,0]
	v_pk_fma_f32 v[52:53], v[184:185], v[152:153], v[52:53] op_sel_hi:[0,1,1]
	v_pk_fma_f32 v[54:55], v[184:185], v[154:155], v[54:55] op_sel_hi:[0,1,1]
	v_pk_fma_f32 v[52:53], v[184:185], v[156:157], v[52:53] op_sel:[1,0,0]
	v_pk_fma_f32 v[54:55], v[184:185], v[158:159], v[54:55] op_sel:[1,0,0]
	ds_read_b128 v[44:47], v94 offset:448
	ds_read_b128 v[48:51], v94 offset:464
	ds_read_b128 v[152:155], v94 offset:480
	ds_read_b128 v[156:159], v94 offset:496
	s_waitcnt lgkmcnt(4)
	v_pk_fma_f32 v[52:53], v[186:187], v[136:137], v[52:53] op_sel_hi:[0,1,1]
	v_pk_fma_f32 v[54:55], v[186:187], v[138:139], v[54:55] op_sel_hi:[0,1,1]
	v_pk_fma_f32 v[52:53], v[186:187], v[140:141], v[52:53] op_sel:[1,0,0]
	v_pk_fma_f32 v[54:55], v[186:187], v[142:143], v[54:55] op_sel:[1,0,0]
	v_pk_fma_f32 v[52:53], v[188:189], v[144:145], v[52:53] op_sel_hi:[0,1,1]
	v_pk_fma_f32 v[54:55], v[188:189], v[146:147], v[54:55] op_sel_hi:[0,1,1]
	v_pk_fma_f32 v[52:53], v[188:189], v[148:149], v[52:53] op_sel:[1,0,0]
	v_pk_fma_f32 v[54:55], v[188:189], v[150:151], v[54:55] op_sel:[1,0,0]
	ds_read_b128 v[136:139], v94 offset:512
	ds_read_b128 v[140:143], v94 offset:528
	ds_read_b128 v[144:147], v94 offset:544
	ds_read_b128 v[148:151], v94 offset:560
	s_waitcnt lgkmcnt(4)
	v_pk_fma_f32 v[52:53], v[190:191], v[44:45], v[52:53] op_sel_hi:[0,1,1]
	v_pk_fma_f32 v[54:55], v[190:191], v[46:47], v[54:55] op_sel_hi:[0,1,1]
	v_pk_fma_f32 v[52:53], v[190:191], v[48:49], v[52:53] op_sel:[1,0,0]
	v_pk_fma_f32 v[54:55], v[190:191], v[50:51], v[54:55] op_sel:[1,0,0]
	v_pk_fma_f32 v[52:53], v[192:193], v[152:153], v[52:53] op_sel_hi:[0,1,1]
	v_pk_fma_f32 v[54:55], v[192:193], v[154:155], v[54:55] op_sel_hi:[0,1,1]
	v_pk_fma_f32 v[52:53], v[192:193], v[156:157], v[52:53] op_sel:[1,0,0]
	v_pk_fma_f32 v[54:55], v[192:193], v[158:159], v[54:55] op_sel:[1,0,0]
	global_load_dwordx4 v[162:165], v[92:93], off offset:2048
	global_load_dwordx4 v[166:169], v[92:93], off offset:2304
	global_load_dwordx4 v[170:173], v[92:93], off offset:2560
	global_load_dwordx4 v[174:177], v[92:93], off offset:2816
	global_load_dwordx4 v[178:181], v[92:93], off offset:3072
	global_load_dwordx4 v[182:185], v[92:93], off offset:3328
	global_load_dwordx4 v[186:189], v[92:93], off offset:3584
	global_load_dwordx4 v[190:193], v[92:93], off offset:3840
	v_lshl_add_u64 v[92:93], v[92:93], 0, s[4:5]
	s_waitcnt vmcnt(16)
	ds_read_b128 v[44:47], v94 offset:576
	ds_read_b128 v[48:51], v94 offset:592
	ds_read_b128 v[152:155], v94 offset:608
	ds_read_b128 v[156:159], v94 offset:624
	s_waitcnt lgkmcnt(4)
	v_pk_fma_f32 v[52:53], v[0:1], v[136:137], v[52:53] op_sel_hi:[0,1,1]
	v_pk_fma_f32 v[54:55], v[0:1], v[138:139], v[54:55] op_sel_hi:[0,1,1]
	v_pk_fma_f32 v[52:53], v[0:1], v[140:141], v[52:53] op_sel:[1,0,0]
	v_pk_fma_f32 v[54:55], v[0:1], v[142:143], v[54:55] op_sel:[1,0,0]
	v_pk_fma_f32 v[52:53], v[2:3], v[144:145], v[52:53] op_sel_hi:[0,1,1]
	v_pk_fma_f32 v[54:55], v[2:3], v[146:147], v[54:55] op_sel_hi:[0,1,1]
	v_pk_fma_f32 v[52:53], v[2:3], v[148:149], v[52:53] op_sel:[1,0,0]
	v_pk_fma_f32 v[54:55], v[2:3], v[150:151], v[54:55] op_sel:[1,0,0]
	ds_read_b128 v[136:139], v94 offset:640
	ds_read_b128 v[140:143], v94 offset:656
	ds_read_b128 v[144:147], v94 offset:672
	ds_read_b128 v[148:151], v94 offset:688
	s_waitcnt lgkmcnt(4)
	v_pk_fma_f32 v[52:53], v[4:5], v[44:45], v[52:53] op_sel_hi:[0,1,1]
	v_pk_fma_f32 v[54:55], v[4:5], v[46:47], v[54:55] op_sel_hi:[0,1,1]
	v_pk_fma_f32 v[52:53], v[4:5], v[48:49], v[52:53] op_sel:[1,0,0]
	v_pk_fma_f32 v[54:55], v[4:5], v[50:51], v[54:55] op_sel:[1,0,0]
	v_pk_fma_f32 v[52:53], v[6:7], v[152:153], v[52:53] op_sel_hi:[0,1,1]
	v_pk_fma_f32 v[54:55], v[6:7], v[154:155], v[54:55] op_sel_hi:[0,1,1]
	v_pk_fma_f32 v[52:53], v[6:7], v[156:157], v[52:53] op_sel:[1,0,0]
	v_pk_fma_f32 v[54:55], v[6:7], v[158:159], v[54:55] op_sel:[1,0,0]
	ds_read_b128 v[44:47], v94 offset:704
	ds_read_b128 v[48:51], v94 offset:720
	ds_read_b128 v[152:155], v94 offset:736
	ds_read_b128 v[156:159], v94 offset:752
	s_waitcnt lgkmcnt(4)
	v_pk_fma_f32 v[52:53], v[8:9], v[136:137], v[52:53] op_sel_hi:[0,1,1]
	v_pk_fma_f32 v[54:55], v[8:9], v[138:139], v[54:55] op_sel_hi:[0,1,1]
	v_pk_fma_f32 v[52:53], v[8:9], v[140:141], v[52:53] op_sel:[1,0,0]
	v_pk_fma_f32 v[54:55], v[8:9], v[142:143], v[54:55] op_sel:[1,0,0]
	v_pk_fma_f32 v[52:53], v[10:11], v[144:145], v[52:53] op_sel_hi:[0,1,1]
	v_pk_fma_f32 v[54:55], v[10:11], v[146:147], v[54:55] op_sel_hi:[0,1,1]
	v_pk_fma_f32 v[52:53], v[10:11], v[148:149], v[52:53] op_sel:[1,0,0]
	v_pk_fma_f32 v[54:55], v[10:11], v[150:151], v[54:55] op_sel:[1,0,0]
	ds_read_b128 v[136:139], v94 offset:768
	ds_read_b128 v[140:143], v94 offset:784
	ds_read_b128 v[144:147], v94 offset:800
	ds_read_b128 v[148:151], v94 offset:816
	s_waitcnt lgkmcnt(4)
; __device__ __forceinline__ void hyena_task(const Params& p, int layer, int c, bool isctx, unsigned char* smem) {
;     ...
;         for (int q = 0; q < 16; q++) {
;           float4 hh = hp[q];
;           a0 += hh.x * misc[4 * q] + hh.y * misc[4 * q + 1] + hh.z * misc[4 * q + 2] + hh.w * misc[4 * q + 3];
;           a1 += hh.x * misc[64 + 4 * q] + hh.y * misc[64 + 4 * q + 1] + hh.z * misc[64 + 4 * q + 2] + hh.w * misc[64 + 4 * q + 3];
;           a2 += hh.x * misc[128 + 4 * q] + hh.y * misc[128 + 4 * q + 1] + hh.z * misc[128 + 4 * q + 2] + hh.w * misc[128 + 4 * q + 3];
;           a3 += hh.x * misc[192 + 4 * q] + hh.y * misc[192 + 4 * q + 1] + hh.z * misc[192 + 4 * q + 2] + hh.w * misc[192 + 4 * q + 3];
;         }
;         float tn = (float)t / (float)Ls;
;         float v0 = (a0 + b3[0]) * expf(-tn * dc[0]), v1 = (a1 + b3[1]) * expf(-tn * dc[1]);
;         float v2 = (a2 + b3[2]) * expf(-tn * dc[2]), v3 = (a3 + b3[3]) * expf(-tn * dc[3]);
;         tmp[t] = v0; tmp[2048 + t] = v1; tmp1[t] = v2; tmp1[2048 + t] = v3;
;         ssq0 += v0 * v0 + v1 * v1; ssq1 += v2 * v2 + v3 * v3;
	v_pk_fma_f32 v[52:53], v[12:13], v[44:45], v[52:53] op_sel_hi:[0,1,1]
	v_pk_fma_f32 v[54:55], v[12:13], v[46:47], v[54:55] op_sel_hi:[0,1,1]
	v_pk_fma_f32 v[52:53], v[12:13], v[48:49], v[52:53] op_sel:[1,0,0]
	v_pk_fma_f32 v[54:55], v[12:13], v[50:51], v[54:55] op_sel:[1,0,0]
	v_pk_fma_f32 v[52:53], v[14:15], v[152:153], v[52:53] op_sel_hi:[0,1,1]
	v_pk_fma_f32 v[54:55], v[14:15], v[154:155], v[54:55] op_sel_hi:[0,1,1]
	v_pk_fma_f32 v[52:53], v[14:15], v[156:157], v[52:53] op_sel:[1,0,0]
	v_pk_fma_f32 v[54:55], v[14:15], v[158:159], v[54:55] op_sel:[1,0,0]
	ds_read_b128 v[44:47], v94 offset:832
	ds_read_b128 v[48:51], v94 offset:848
	ds_read_b128 v[152:155], v94 offset:864
	ds_read_b128 v[156:159], v94 offset:880
	s_waitcnt lgkmcnt(4)
	v_pk_fma_f32 v[52:53], v[16:17], v[136:137], v[52:53] op_sel_hi:[0,1,1]
	v_pk_fma_f32 v[54:55], v[16:17], v[138:139], v[54:55] op_sel_hi:[0,1,1]
	v_pk_fma_f32 v[52:53], v[16:17], v[140:141], v[52:53] op_sel:[1,0,0]
	v_pk_fma_f32 v[54:55], v[16:17], v[142:143], v[54:55] op_sel:[1,0,0]
	v_pk_fma_f32 v[52:53], v[18:19], v[144:145], v[52:53] op_sel_hi:[0,1,1]
	v_pk_fma_f32 v[54:55], v[18:19], v[146:147], v[54:55] op_sel_hi:[0,1,1]
	v_pk_fma_f32 v[52:53], v[18:19], v[148:149], v[52:53] op_sel:[1,0,0]
	v_pk_fma_f32 v[54:55], v[18:19], v[150:151], v[54:55] op_sel:[1,0,0]
	ds_read_b128 v[136:139], v94 offset:896
	ds_read_b128 v[140:143], v94 offset:912
	ds_read_b128 v[144:147], v94 offset:928
	ds_read_b128 v[148:151], v94 offset:944
	s_waitcnt lgkmcnt(4)
	v_pk_fma_f32 v[52:53], v[20:21], v[44:45], v[52:53] op_sel_hi:[0,1,1]
	v_pk_fma_f32 v[54:55], v[20:21], v[46:47], v[54:55] op_sel_hi:[0,1,1]
	v_pk_fma_f32 v[52:53], v[20:21], v[48:49], v[52:53] op_sel:[1,0,0]
	v_pk_fma_f32 v[54:55], v[20:21], v[50:51], v[54:55] op_sel:[1,0,0]
	v_pk_fma_f32 v[52:53], v[22:23], v[152:153], v[52:53] op_sel_hi:[0,1,1]
	v_pk_fma_f32 v[54:55], v[22:23], v[154:155], v[54:55] op_sel_hi:[0,1,1]
	v_pk_fma_f32 v[52:53], v[22:23], v[156:157], v[52:53] op_sel:[1,0,0]
	v_pk_fma_f32 v[54:55], v[22:23], v[158:159], v[54:55] op_sel:[1,0,0]
	ds_read_b128 v[44:47], v94 offset:960
	ds_read_b128 v[48:51], v94 offset:976
	ds_read_b128 v[152:155], v94 offset:992
	ds_read_b128 v[156:159], v94 offset:1008
	s_waitcnt lgkmcnt(4)
	v_pk_fma_f32 v[52:53], v[24:25], v[136:137], v[52:53] op_sel_hi:[0,1,1]
	v_pk_fma_f32 v[54:55], v[24:25], v[138:139], v[54:55] op_sel_hi:[0,1,1]
	v_pk_fma_f32 v[52:53], v[24:25], v[140:141], v[52:53] op_sel:[1,0,0]
	v_pk_fma_f32 v[54:55], v[24:25], v[142:143], v[54:55] op_sel:[1,0,0]
	v_pk_fma_f32 v[52:53], v[26:27], v[144:145], v[52:53] op_sel_hi:[0,1,1]
	v_pk_fma_f32 v[54:55], v[26:27], v[146:147], v[54:55] op_sel_hi:[0,1,1]
	v_pk_fma_f32 v[52:53], v[26:27], v[148:149], v[52:53] op_sel:[1,0,0]
	v_pk_fma_f32 v[54:55], v[26:27], v[150:151], v[54:55] op_sel:[1,0,0]
	ds_read_b128 v[136:139], v94
	ds_read_b128 v[140:143], v94 offset:16
	ds_read_b128 v[144:147], v94 offset:32
	ds_read_b128 v[148:151], v94 offset:48
	s_waitcnt lgkmcnt(4)
	v_pk_fma_f32 v[52:53], v[28:29], v[44:45], v[52:53] op_sel_hi:[0,1,1]
	v_pk_fma_f32 v[54:55], v[28:29], v[46:47], v[54:55] op_sel_hi:[0,1,1]
	v_pk_fma_f32 v[52:53], v[28:29], v[48:49], v[52:53] op_sel:[1,0,0]
	v_pk_fma_f32 v[54:55], v[28:29], v[50:51], v[54:55] op_sel:[1,0,0]
	v_pk_fma_f32 v[52:53], v[30:31], v[152:153], v[52:53] op_sel_hi:[0,1,1]
	v_pk_fma_f32 v[54:55], v[30:31], v[154:155], v[54:55] op_sel_hi:[0,1,1]
	v_pk_fma_f32 v[52:53], v[30:31], v[156:157], v[52:53] op_sel:[1,0,0]
	v_pk_fma_f32 v[54:55], v[30:31], v[158:159], v[54:55] op_sel:[1,0,0]
	v_mov_b32_e32 v100, v66
	v_cvt_f32_i32_e32 v100, v100
	v_mul_f32_e32 v95, 0xba000000, v100
	v_mul_f32_e32 v96, v131, v95
	v_mul_f32_e32 v97, 0x3fb8aa3b, v96
	v_fma_f32 v100, v96, s55, -v97
	v_rndne_f32_e32 v101, v97
	v_fmac_f32_e32 v100, 0x32a5705f, v96
	v_sub_f32_e32 v97, v97, v101
	v_add_f32_e32 v97, v97, v100
	v_exp_f32_e32 v97, v97
	v_cvt_i32_f32_e32 v101, v101
	v_cmp_ngt_f32_e32 vcc, s56, v96
	v_ldexp_f32 v97, v97, v101
	s_nop 0
	v_cndmask_b32_e32 v97, 0, v97, vcc
	v_cmp_nlt_f32_e32 vcc, s54, v96
	v_add_f32_e32 v52, v89, v52
	s_nop 0
	v_cndmask_b32_e32 v97, v242, v97, vcc
	v_mul_f32_e32 v52, v52, v97
	v_mul_f32_e32 v96, v132, v95
	v_mul_f32_e32 v97, 0x3fb8aa3b, v96
	v_fma_f32 v100, v96, s55, -v97
	v_rndne_f32_e32 v101, v97
	v_fmac_f32_e32 v100, 0x32a5705f, v96
	v_sub_f32_e32 v97, v97, v101
	v_add_f32_e32 v97, v97, v100
	v_exp_f32_e32 v97, v97
	v_cvt_i32_f32_e32 v101, v101
	v_cmp_ngt_f32_e32 vcc, s56, v96
	v_ldexp_f32 v97, v97, v101
	s_nop 0
	v_cndmask_b32_e32 v97, 0, v97, vcc
	v_cmp_nlt_f32_e32 vcc, s54, v96
	v_add_f32_e32 v53, v91, v53
	s_nop 0
	v_cndmask_b32_e32 v97, v242, v97, vcc
	v_mul_f32_e32 v53, v53, v97
	v_mul_f32_e32 v96, v133, v95
	v_mul_f32_e32 v97, 0x3fb8aa3b, v96
	v_fma_f32 v100, v96, s55, -v97
	v_rndne_f32_e32 v101, v97
	v_fmac_f32_e32 v100, 0x32a5705f, v96
	v_sub_f32_e32 v97, v97, v101
	v_add_f32_e32 v97, v97, v100
	v_exp_f32_e32 v97, v97
	v_cvt_i32_f32_e32 v101, v101
	v_cmp_ngt_f32_e32 vcc, s56, v96
	v_ldexp_f32 v97, v97, v101
	s_nop 0
	v_cndmask_b32_e32 v97, 0, v97, vcc
	v_cmp_nlt_f32_e32 vcc, s54, v96
	v_add_f32_e32 v54, v88, v54
	s_nop 0
	v_cndmask_b32_e32 v97, v242, v97, vcc
	v_mul_f32_e32 v54, v54, v97
	v_mul_f32_e32 v96, v134, v95
	v_mul_f32_e32 v97, 0x3fb8aa3b, v96
	v_fma_f32 v100, v96, s55, -v97
	v_rndne_f32_e32 v101, v97
	v_fmac_f32_e32 v100, 0x32a5705f, v96
	v_sub_f32_e32 v97, v97, v101
	v_add_f32_e32 v97, v97, v100
	v_exp_f32_e32 v97, v97
	v_cvt_i32_f32_e32 v101, v101
	v_cmp_ngt_f32_e32 vcc, s56, v96
	v_ldexp_f32 v97, v97, v101
	s_nop 0
	v_cndmask_b32_e32 v97, 0, v97, vcc
	v_cmp_nlt_f32_e32 vcc, s54, v96
	v_add_f32_e32 v55, v90, v55
	s_nop 0
	v_cndmask_b32_e32 v97, v242, v97, vcc
	v_mul_f32_e32 v55, v55, v97
	ds_write_b32 v98, v52 offset:33024
	ds_write_b32 v98, v53 offset:41216
	ds_write_b32 v99, v54
	ds_write_b32 v99, v55 offset:8192
	v_fmac_f32_e32 v65, v52, v52
	v_fmac_f32_e32 v65, v53, v53
	v_fmac_f32_e32 v64, v54, v54
	v_fmac_f32_e32 v64, v55, v55
	v_mov_b32_e32 v52, 0
	v_mov_b32_e32 v53, 0
	v_mov_b32_e32 v54, 0
	v_mov_b32_e32 v55, 0
	global_load_dwordx4 v[0:3], v[92:93], off
	global_load_dwordx4 v[4:7], v[92:93], off offset:256
	global_load_dwordx4 v[8:11], v[92:93], off offset:512
	global_load_dwordx4 v[12:15], v[92:93], off offset:768
	global_load_dwordx4 v[16:19], v[92:93], off offset:1024
	global_load_dwordx4 v[20:23], v[92:93], off offset:1280
	global_load_dwordx4 v[24:27], v[92:93], off offset:1536
	global_load_dwordx4 v[28:31], v[92:93], off offset:1792
	s_waitcnt vmcnt(16)
; __device__ __forceinline__ void hyena_task(const Params& p, int layer, int c, bool isctx, unsigned char* smem) {
;     ...
;         for (int q = 0; q < 16; q++) {
;           float4 hh = hp[q];
;           a0 += hh.x * misc[4 * q] + hh.y * misc[4 * q + 1] + hh.z * misc[4 * q + 2] + hh.w * misc[4 * q + 3];
;           a1 += hh.x * misc[64 + 4 * q] + hh.y * misc[64 + 4 * q + 1] + hh.z * misc[64 + 4 * q + 2] + hh.w * misc[64 + 4 * q + 3];
;           a2 += hh.x * misc[128 + 4 * q] + hh.y * misc[128 + 4 * q + 1] + hh.z * misc[128 + 4 * q + 2] + hh.w * misc[128 + 4 * q + 3];
;           a3 += hh.x * misc[192 + 4 * q] + hh.y * misc[192 + 4 * q + 1] + hh.z * misc[192 + 4 * q + 2] + hh.w * misc[192 + 4 * q + 3];
;         }
	ds_read_b128 v[44:47], v94 offset:64
	ds_read_b128 v[48:51], v94 offset:80
	ds_read_b128 v[152:155], v94 offset:96
	ds_read_b128 v[156:159], v94 offset:112
	s_waitcnt lgkmcnt(4)
	v_pk_fma_f32 v[52:53], v[194:195], v[136:137], v[52:53] op_sel_hi:[0,1,1]
	v_pk_fma_f32 v[54:55], v[194:195], v[138:139], v[54:55] op_sel_hi:[0,1,1]
	v_pk_fma_f32 v[52:53], v[194:195], v[140:141], v[52:53] op_sel:[1,0,0]
	v_pk_fma_f32 v[54:55], v[194:195], v[142:143], v[54:55] op_sel:[1,0,0]
	v_pk_fma_f32 v[52:53], v[196:197], v[144:145], v[52:53] op_sel_hi:[0,1,1]
	v_pk_fma_f32 v[54:55], v[196:197], v[146:147], v[54:55] op_sel_hi:[0,1,1]
	v_pk_fma_f32 v[52:53], v[196:197], v[148:149], v[52:53] op_sel:[1,0,0]
	v_pk_fma_f32 v[54:55], v[196:197], v[150:151], v[54:55] op_sel:[1,0,0]
	ds_read_b128 v[136:139], v94 offset:128
	ds_read_b128 v[140:143], v94 offset:144
	ds_read_b128 v[144:147], v94 offset:160
	ds_read_b128 v[148:151], v94 offset:176
	s_waitcnt lgkmcnt(4)
	v_pk_fma_f32 v[52:53], v[198:199], v[44:45], v[52:53] op_sel_hi:[0,1,1]
	v_pk_fma_f32 v[54:55], v[198:199], v[46:47], v[54:55] op_sel_hi:[0,1,1]
	v_pk_fma_f32 v[52:53], v[198:199], v[48:49], v[52:53] op_sel:[1,0,0]
	v_pk_fma_f32 v[54:55], v[198:199], v[50:51], v[54:55] op_sel:[1,0,0]
	v_pk_fma_f32 v[52:53], v[200:201], v[152:153], v[52:53] op_sel_hi:[0,1,1]
	v_pk_fma_f32 v[54:55], v[200:201], v[154:155], v[54:55] op_sel_hi:[0,1,1]
	v_pk_fma_f32 v[52:53], v[200:201], v[156:157], v[52:53] op_sel:[1,0,0]
	v_pk_fma_f32 v[54:55], v[200:201], v[158:159], v[54:55] op_sel:[1,0,0]
	ds_read_b128 v[44:47], v94 offset:192
	ds_read_b128 v[48:51], v94 offset:208
	ds_read_b128 v[152:155], v94 offset:224
	ds_read_b128 v[156:159], v94 offset:240
	s_waitcnt lgkmcnt(4)
	v_pk_fma_f32 v[52:53], v[202:203], v[136:137], v[52:53] op_sel_hi:[0,1,1]
	v_pk_fma_f32 v[54:55], v[202:203], v[138:139], v[54:55] op_sel_hi:[0,1,1]
	v_pk_fma_f32 v[52:53], v[202:203], v[140:141], v[52:53] op_sel:[1,0,0]
	v_pk_fma_f32 v[54:55], v[202:203], v[142:143], v[54:55] op_sel:[1,0,0]
	v_pk_fma_f32 v[52:53], v[204:205], v[144:145], v[52:53] op_sel_hi:[0,1,1]
	v_pk_fma_f32 v[54:55], v[204:205], v[146:147], v[54:55] op_sel_hi:[0,1,1]
	v_pk_fma_f32 v[52:53], v[204:205], v[148:149], v[52:53] op_sel:[1,0,0]
	v_pk_fma_f32 v[54:55], v[204:205], v[150:151], v[54:55] op_sel:[1,0,0]
	ds_read_b128 v[136:139], v94 offset:256
	ds_read_b128 v[140:143], v94 offset:272
	ds_read_b128 v[144:147], v94 offset:288
	ds_read_b128 v[148:151], v94 offset:304
	s_waitcnt lgkmcnt(4)
	v_pk_fma_f32 v[52:53], v[206:207], v[44:45], v[52:53] op_sel_hi:[0,1,1]
	v_pk_fma_f32 v[54:55], v[206:207], v[46:47], v[54:55] op_sel_hi:[0,1,1]
	v_pk_fma_f32 v[52:53], v[206:207], v[48:49], v[52:53] op_sel:[1,0,0]
	v_pk_fma_f32 v[54:55], v[206:207], v[50:51], v[54:55] op_sel:[1,0,0]
	v_pk_fma_f32 v[52:53], v[208:209], v[152:153], v[52:53] op_sel_hi:[0,1,1]
	v_pk_fma_f32 v[54:55], v[208:209], v[154:155], v[54:55] op_sel_hi:[0,1,1]
	v_pk_fma_f32 v[52:53], v[208:209], v[156:157], v[52:53] op_sel:[1,0,0]
	v_pk_fma_f32 v[54:55], v[208:209], v[158:159], v[54:55] op_sel:[1,0,0]
	ds_read_b128 v[44:47], v94 offset:320
	ds_read_b128 v[48:51], v94 offset:336
	ds_read_b128 v[152:155], v94 offset:352
	ds_read_b128 v[156:159], v94 offset:368
	s_waitcnt lgkmcnt(4)
	v_pk_fma_f32 v[52:53], v[210:211], v[136:137], v[52:53] op_sel_hi:[0,1,1]
	v_pk_fma_f32 v[54:55], v[210:211], v[138:139], v[54:55] op_sel_hi:[0,1,1]
	v_pk_fma_f32 v[52:53], v[210:211], v[140:141], v[52:53] op_sel:[1,0,0]
	v_pk_fma_f32 v[54:55], v[210:211], v[142:143], v[54:55] op_sel:[1,0,0]
	v_pk_fma_f32 v[52:53], v[212:213], v[144:145], v[52:53] op_sel_hi:[0,1,1]
	v_pk_fma_f32 v[54:55], v[212:213], v[146:147], v[54:55] op_sel_hi:[0,1,1]
	v_pk_fma_f32 v[52:53], v[212:213], v[148:149], v[52:53] op_sel:[1,0,0]
	v_pk_fma_f32 v[54:55], v[212:213], v[150:151], v[54:55] op_sel:[1,0,0]
	ds_read_b128 v[136:139], v94 offset:384
	ds_read_b128 v[140:143], v94 offset:400
	ds_read_b128 v[144:147], v94 offset:416
	ds_read_b128 v[148:151], v94 offset:432
	s_waitcnt lgkmcnt(4)
	v_pk_fma_f32 v[52:53], v[32:33], v[44:45], v[52:53] op_sel_hi:[0,1,1]
	v_pk_fma_f32 v[54:55], v[32:33], v[46:47], v[54:55] op_sel_hi:[0,1,1]
	v_pk_fma_f32 v[52:53], v[32:33], v[48:49], v[52:53] op_sel:[1,0,0]
	v_pk_fma_f32 v[54:55], v[32:33], v[50:51], v[54:55] op_sel:[1,0,0]
	v_pk_fma_f32 v[52:53], v[34:35], v[152:153], v[52:53] op_sel_hi:[0,1,1]
	v_pk_fma_f32 v[54:55], v[34:35], v[154:155], v[54:55] op_sel_hi:[0,1,1]
	v_pk_fma_f32 v[52:53], v[34:35], v[156:157], v[52:53] op_sel:[1,0,0]
	v_pk_fma_f32 v[54:55], v[34:35], v[158:159], v[54:55] op_sel:[1,0,0]
	ds_read_b128 v[44:47], v94 offset:448
	ds_read_b128 v[48:51], v94 offset:464
	ds_read_b128 v[152:155], v94 offset:480
	ds_read_b128 v[156:159], v94 offset:496
	s_waitcnt lgkmcnt(4)
	v_pk_fma_f32 v[52:53], v[36:37], v[136:137], v[52:53] op_sel_hi:[0,1,1]
	v_pk_fma_f32 v[54:55], v[36:37], v[138:139], v[54:55] op_sel_hi:[0,1,1]
	v_pk_fma_f32 v[52:53], v[36:37], v[140:141], v[52:53] op_sel:[1,0,0]
	v_pk_fma_f32 v[54:55], v[36:37], v[142:143], v[54:55] op_sel:[1,0,0]
	v_pk_fma_f32 v[52:53], v[38:39], v[144:145], v[52:53] op_sel_hi:[0,1,1]
	v_pk_fma_f32 v[54:55], v[38:39], v[146:147], v[54:55] op_sel_hi:[0,1,1]
	v_pk_fma_f32 v[52:53], v[38:39], v[148:149], v[52:53] op_sel:[1,0,0]
	v_pk_fma_f32 v[54:55], v[38:39], v[150:151], v[54:55] op_sel:[1,0,0]
	ds_read_b128 v[136:139], v94 offset:512
	ds_read_b128 v[140:143], v94 offset:528
	ds_read_b128 v[144:147], v94 offset:544
	ds_read_b128 v[148:151], v94 offset:560
	s_waitcnt lgkmcnt(4)
; __device__ __forceinline__ void hyena_task(const Params& p, int layer, int c, bool isctx, unsigned char* smem) {
;     ...
;         for (int q = 0; q < 16; q++) {
;           float4 hh = hp[q];
;           a0 += hh.x * misc[4 * q] + hh.y * misc[4 * q + 1] + hh.z * misc[4 * q + 2] + hh.w * misc[4 * q + 3];
;           a1 += hh.x * misc[64 + 4 * q] + hh.y * misc[64 + 4 * q + 1] + hh.z * misc[64 + 4 * q + 2] + hh.w * misc[64 + 4 * q + 3];
;           a2 += hh.x * misc[128 + 4 * q] + hh.y * misc[128 + 4 * q + 1] + hh.z * misc[128 + 4 * q + 2] + hh.w * misc[128 + 4 * q + 3];
;           a3 += hh.x * misc[192 + 4 * q] + hh.y * misc[192 + 4 * q + 1] + hh.z * misc[192 + 4 * q + 2] + hh.w * misc[192 + 4 * q + 3];
;         }
	v_pk_fma_f32 v[52:53], v[40:41], v[44:45], v[52:53] op_sel_hi:[0,1,1]
	v_pk_fma_f32 v[54:55], v[40:41], v[46:47], v[54:55] op_sel_hi:[0,1,1]
	v_pk_fma_f32 v[52:53], v[40:41], v[48:49], v[52:53] op_sel:[1,0,0]
	v_pk_fma_f32 v[54:55], v[40:41], v[50:51], v[54:55] op_sel:[1,0,0]
	v_pk_fma_f32 v[52:53], v[42:43], v[152:153], v[52:53] op_sel_hi:[0,1,1]
	v_pk_fma_f32 v[54:55], v[42:43], v[154:155], v[54:55] op_sel_hi:[0,1,1]
	v_pk_fma_f32 v[52:53], v[42:43], v[156:157], v[52:53] op_sel:[1,0,0]
	v_pk_fma_f32 v[54:55], v[42:43], v[158:159], v[54:55] op_sel:[1,0,0]
	global_load_dwordx4 v[194:197], v[92:93], off offset:2048
	global_load_dwordx4 v[198:201], v[92:93], off offset:2304
	global_load_dwordx4 v[202:205], v[92:93], off offset:2560
	global_load_dwordx4 v[206:209], v[92:93], off offset:2816
	global_load_dwordx4 v[210:213], v[92:93], off offset:3072
	global_load_dwordx4 v[32:35], v[92:93], off offset:3328
	global_load_dwordx4 v[36:39], v[92:93], off offset:3584
	global_load_dwordx4 v[40:43], v[92:93], off offset:3840
	v_lshl_add_u64 v[92:93], v[92:93], 0, s[4:5]
	s_waitcnt vmcnt(16)
	ds_read_b128 v[44:47], v94 offset:576
	ds_read_b128 v[48:51], v94 offset:592
	ds_read_b128 v[152:155], v94 offset:608
	ds_read_b128 v[156:159], v94 offset:624
	s_waitcnt lgkmcnt(4)
	v_pk_fma_f32 v[52:53], v[162:163], v[136:137], v[52:53] op_sel_hi:[0,1,1]
	v_pk_fma_f32 v[54:55], v[162:163], v[138:139], v[54:55] op_sel_hi:[0,1,1]
	v_pk_fma_f32 v[52:53], v[162:163], v[140:141], v[52:53] op_sel:[1,0,0]
	v_pk_fma_f32 v[54:55], v[162:163], v[142:143], v[54:55] op_sel:[1,0,0]
	v_pk_fma_f32 v[52:53], v[164:165], v[144:145], v[52:53] op_sel_hi:[0,1,1]
	v_pk_fma_f32 v[54:55], v[164:165], v[146:147], v[54:55] op_sel_hi:[0,1,1]
	v_pk_fma_f32 v[52:53], v[164:165], v[148:149], v[52:53] op_sel:[1,0,0]
	v_pk_fma_f32 v[54:55], v[164:165], v[150:151], v[54:55] op_sel:[1,0,0]
	ds_read_b128 v[136:139], v94 offset:640
	ds_read_b128 v[140:143], v94 offset:656
	ds_read_b128 v[144:147], v94 offset:672
	ds_read_b128 v[148:151], v94 offset:688
	s_waitcnt lgkmcnt(4)
	v_pk_fma_f32 v[52:53], v[166:167], v[44:45], v[52:53] op_sel_hi:[0,1,1]
	v_pk_fma_f32 v[54:55], v[166:167], v[46:47], v[54:55] op_sel_hi:[0,1,1]
	v_pk_fma_f32 v[52:53], v[166:167], v[48:49], v[52:53] op_sel:[1,0,0]
	v_pk_fma_f32 v[54:55], v[166:167], v[50:51], v[54:55] op_sel:[1,0,0]
	v_pk_fma_f32 v[52:53], v[168:169], v[152:153], v[52:53] op_sel_hi:[0,1,1]
	v_pk_fma_f32 v[54:55], v[168:169], v[154:155], v[54:55] op_sel_hi:[0,1,1]
	v_pk_fma_f32 v[52:53], v[168:169], v[156:157], v[52:53] op_sel:[1,0,0]
	v_pk_fma_f32 v[54:55], v[168:169], v[158:159], v[54:55] op_sel:[1,0,0]
	ds_read_b128 v[44:47], v94 offset:704
	ds_read_b128 v[48:51], v94 offset:720
	ds_read_b128 v[152:155], v94 offset:736
	ds_read_b128 v[156:159], v94 offset:752
	s_waitcnt lgkmcnt(4)
	v_pk_fma_f32 v[52:53], v[170:171], v[136:137], v[52:53] op_sel_hi:[0,1,1]
	v_pk_fma_f32 v[54:55], v[170:171], v[138:139], v[54:55] op_sel_hi:[0,1,1]
	v_pk_fma_f32 v[52:53], v[170:171], v[140:141], v[52:53] op_sel:[1,0,0]
	v_pk_fma_f32 v[54:55], v[170:171], v[142:143], v[54:55] op_sel:[1,0,0]
	v_pk_fma_f32 v[52:53], v[172:173], v[144:145], v[52:53] op_sel_hi:[0,1,1]
	v_pk_fma_f32 v[54:55], v[172:173], v[146:147], v[54:55] op_sel_hi:[0,1,1]
	v_pk_fma_f32 v[52:53], v[172:173], v[148:149], v[52:53] op_sel:[1,0,0]
	v_pk_fma_f32 v[54:55], v[172:173], v[150:151], v[54:55] op_sel:[1,0,0]
	ds_read_b128 v[136:139], v94 offset:768
	ds_read_b128 v[140:143], v94 offset:784
	ds_read_b128 v[144:147], v94 offset:800
	ds_read_b128 v[148:151], v94 offset:816
	s_waitcnt lgkmcnt(4)
	v_pk_fma_f32 v[52:53], v[174:175], v[44:45], v[52:53] op_sel_hi:[0,1,1]
	v_pk_fma_f32 v[54:55], v[174:175], v[46:47], v[54:55] op_sel_hi:[0,1,1]
	v_pk_fma_f32 v[52:53], v[174:175], v[48:49], v[52:53] op_sel:[1,0,0]
	v_pk_fma_f32 v[54:55], v[174:175], v[50:51], v[54:55] op_sel:[1,0,0]
	v_pk_fma_f32 v[52:53], v[176:177], v[152:153], v[52:53] op_sel_hi:[0,1,1]
	v_pk_fma_f32 v[54:55], v[176:177], v[154:155], v[54:55] op_sel_hi:[0,1,1]
	v_pk_fma_f32 v[52:53], v[176:177], v[156:157], v[52:53] op_sel:[1,0,0]
	v_pk_fma_f32 v[54:55], v[176:177], v[158:159], v[54:55] op_sel:[1,0,0]
	ds_read_b128 v[44:47], v94 offset:832
	ds_read_b128 v[48:51], v94 offset:848
	ds_read_b128 v[152:155], v94 offset:864
	ds_read_b128 v[156:159], v94 offset:880
	s_waitcnt lgkmcnt(4)
	v_pk_fma_f32 v[52:53], v[178:179], v[136:137], v[52:53] op_sel_hi:[0,1,1]
	v_pk_fma_f32 v[54:55], v[178:179], v[138:139], v[54:55] op_sel_hi:[0,1,1]
	v_pk_fma_f32 v[52:53], v[178:179], v[140:141], v[52:53] op_sel:[1,0,0]
	v_pk_fma_f32 v[54:55], v[178:179], v[142:143], v[54:55] op_sel:[1,0,0]
	v_pk_fma_f32 v[52:53], v[180:181], v[144:145], v[52:53] op_sel_hi:[0,1,1]
	v_pk_fma_f32 v[54:55], v[180:181], v[146:147], v[54:55] op_sel_hi:[0,1,1]
	v_pk_fma_f32 v[52:53], v[180:181], v[148:149], v[52:53] op_sel:[1,0,0]
	v_pk_fma_f32 v[54:55], v[180:181], v[150:151], v[54:55] op_sel:[1,0,0]
	ds_read_b128 v[136:139], v94 offset:896
	ds_read_b128 v[140:143], v94 offset:912
	ds_read_b128 v[144:147], v94 offset:928
	ds_read_b128 v[148:151], v94 offset:944
	s_waitcnt lgkmcnt(4)
	v_pk_fma_f32 v[52:53], v[182:183], v[44:45], v[52:53] op_sel_hi:[0,1,1]
	v_pk_fma_f32 v[54:55], v[182:183], v[46:47], v[54:55] op_sel_hi:[0,1,1]
	v_pk_fma_f32 v[52:53], v[182:183], v[48:49], v[52:53] op_sel:[1,0,0]
	v_pk_fma_f32 v[54:55], v[182:183], v[50:51], v[54:55] op_sel:[1,0,0]
	v_pk_fma_f32 v[52:53], v[184:185], v[152:153], v[52:53] op_sel_hi:[0,1,1]
	v_pk_fma_f32 v[54:55], v[184:185], v[154:155], v[54:55] op_sel_hi:[0,1,1]
	v_pk_fma_f32 v[52:53], v[184:185], v[156:157], v[52:53] op_sel:[1,0,0]
	v_pk_fma_f32 v[54:55], v[184:185], v[158:159], v[54:55] op_sel:[1,0,0]
	ds_read_b128 v[44:47], v94 offset:960
	ds_read_b128 v[48:51], v94 offset:976
	ds_read_b128 v[152:155], v94 offset:992
	ds_read_b128 v[156:159], v94 offset:1008
	s_waitcnt lgkmcnt(4)
; __device__ __forceinline__ void hyena_task(const Params& p, int layer, int c, bool isctx, unsigned char* smem) {
;     ...
;         for (int q = 0; q < 16; q++) {
;           float4 hh = hp[q];
;           a0 += hh.x * misc[4 * q] + hh.y * misc[4 * q + 1] + hh.z * misc[4 * q + 2] + hh.w * misc[4 * q + 3];
;           a1 += hh.x * misc[64 + 4 * q] + hh.y * misc[64 + 4 * q + 1] + hh.z * misc[64 + 4 * q + 2] + hh.w * misc[64 + 4 * q + 3];
;           a2 += hh.x * misc[128 + 4 * q] + hh.y * misc[128 + 4 * q + 1] + hh.z * misc[128 + 4 * q + 2] + hh.w * misc[128 + 4 * q + 3];
;           a3 += hh.x * misc[192 + 4 * q] + hh.y * misc[192 + 4 * q + 1] + hh.z * misc[192 + 4 * q + 2] + hh.w * misc[192 + 4 * q + 3];
;         }
;         float tn = (float)t / (float)Ls;
;         float v0 = (a0 + b3[0]) * expf(-tn * dc[0]), v1 = (a1 + b3[1]) * expf(-tn * dc[1]);
;         float v2 = (a2 + b3[2]) * expf(-tn * dc[2]), v3 = (a3 + b3[3]) * expf(-tn * dc[3]);
;         tmp[t] = v0; tmp[2048 + t] = v1; tmp1[t] = v2; tmp1[2048 + t] = v3;
;         ssq0 += v0 * v0 + v1 * v1; ssq1 += v2 * v2 + v3 * v3;
	v_pk_fma_f32 v[52:53], v[186:187], v[136:137], v[52:53] op_sel_hi:[0,1,1]
	v_pk_fma_f32 v[54:55], v[186:187], v[138:139], v[54:55] op_sel_hi:[0,1,1]
	v_pk_fma_f32 v[52:53], v[186:187], v[140:141], v[52:53] op_sel:[1,0,0]
	v_pk_fma_f32 v[54:55], v[186:187], v[142:143], v[54:55] op_sel:[1,0,0]
	v_pk_fma_f32 v[52:53], v[188:189], v[144:145], v[52:53] op_sel_hi:[0,1,1]
	v_pk_fma_f32 v[54:55], v[188:189], v[146:147], v[54:55] op_sel_hi:[0,1,1]
	v_pk_fma_f32 v[52:53], v[188:189], v[148:149], v[52:53] op_sel:[1,0,0]
	v_pk_fma_f32 v[54:55], v[188:189], v[150:151], v[54:55] op_sel:[1,0,0]
	ds_read_b128 v[136:139], v94
	ds_read_b128 v[140:143], v94 offset:16
	ds_read_b128 v[144:147], v94 offset:32
	ds_read_b128 v[148:151], v94 offset:48
	s_waitcnt lgkmcnt(4)
	v_pk_fma_f32 v[52:53], v[190:191], v[44:45], v[52:53] op_sel_hi:[0,1,1]
	v_pk_fma_f32 v[54:55], v[190:191], v[46:47], v[54:55] op_sel_hi:[0,1,1]
	v_pk_fma_f32 v[52:53], v[190:191], v[48:49], v[52:53] op_sel:[1,0,0]
	v_pk_fma_f32 v[54:55], v[190:191], v[50:51], v[54:55] op_sel:[1,0,0]
	v_pk_fma_f32 v[52:53], v[192:193], v[152:153], v[52:53] op_sel_hi:[0,1,1]
	v_pk_fma_f32 v[54:55], v[192:193], v[154:155], v[54:55] op_sel_hi:[0,1,1]
	v_pk_fma_f32 v[52:53], v[192:193], v[156:157], v[52:53] op_sel:[1,0,0]
	v_pk_fma_f32 v[54:55], v[192:193], v[158:159], v[54:55] op_sel:[1,0,0]
	v_add_u32_e32 v100, 0x200, v66
	v_cvt_f32_i32_e32 v100, v100
	v_mul_f32_e32 v95, 0xba000000, v100
	v_mul_f32_e32 v96, v131, v95
	v_mul_f32_e32 v97, 0x3fb8aa3b, v96
	v_fma_f32 v100, v96, s55, -v97
	v_rndne_f32_e32 v101, v97
	v_fmac_f32_e32 v100, 0x32a5705f, v96
	v_sub_f32_e32 v97, v97, v101
	v_add_f32_e32 v97, v97, v100
	v_exp_f32_e32 v97, v97
	v_cvt_i32_f32_e32 v101, v101
	v_cmp_ngt_f32_e32 vcc, s56, v96
	v_ldexp_f32 v97, v97, v101
	s_nop 0
	v_cndmask_b32_e32 v97, 0, v97, vcc
	v_cmp_nlt_f32_e32 vcc, s54, v96
	v_add_f32_e32 v52, v89, v52
	s_nop 0
	v_cndmask_b32_e32 v97, v242, v97, vcc
	v_mul_f32_e32 v52, v52, v97
	v_mul_f32_e32 v96, v132, v95
	v_mul_f32_e32 v97, 0x3fb8aa3b, v96
	v_fma_f32 v100, v96, s55, -v97
	v_rndne_f32_e32 v101, v97
	v_fmac_f32_e32 v100, 0x32a5705f, v96
	v_sub_f32_e32 v97, v97, v101
	v_add_f32_e32 v97, v97, v100
	v_exp_f32_e32 v97, v97
	v_cvt_i32_f32_e32 v101, v101
	v_cmp_ngt_f32_e32 vcc, s56, v96
	v_ldexp_f32 v97, v97, v101
	s_nop 0
	v_cndmask_b32_e32 v97, 0, v97, vcc
	v_cmp_nlt_f32_e32 vcc, s54, v96
	v_add_f32_e32 v53, v91, v53
	s_nop 0
	v_cndmask_b32_e32 v97, v242, v97, vcc
	v_mul_f32_e32 v53, v53, v97
	v_mul_f32_e32 v96, v133, v95
	v_mul_f32_e32 v97, 0x3fb8aa3b, v96
	v_fma_f32 v100, v96, s55, -v97
	v_rndne_f32_e32 v101, v97
	v_fmac_f32_e32 v100, 0x32a5705f, v96
	v_sub_f32_e32 v97, v97, v101
	v_add_f32_e32 v97, v97, v100
	v_exp_f32_e32 v97, v97
	v_cvt_i32_f32_e32 v101, v101
	v_cmp_ngt_f32_e32 vcc, s56, v96
	v_ldexp_f32 v97, v97, v101
	s_nop 0
	v_cndmask_b32_e32 v97, 0, v97, vcc
	v_cmp_nlt_f32_e32 vcc, s54, v96
	v_add_f32_e32 v54, v88, v54
	s_nop 0
	v_cndmask_b32_e32 v97, v242, v97, vcc
	v_mul_f32_e32 v54, v54, v97
	v_mul_f32_e32 v96, v134, v95
	v_mul_f32_e32 v97, 0x3fb8aa3b, v96
	v_fma_f32 v100, v96, s55, -v97
	v_rndne_f32_e32 v101, v97
	v_fmac_f32_e32 v100, 0x32a5705f, v96
	v_sub_f32_e32 v97, v97, v101
	v_add_f32_e32 v97, v97, v100
	v_exp_f32_e32 v97, v97
	v_cvt_i32_f32_e32 v101, v101
	v_cmp_ngt_f32_e32 vcc, s56, v96
	v_ldexp_f32 v97, v97, v101
	s_nop 0
	v_cndmask_b32_e32 v97, 0, v97, vcc
	v_cmp_nlt_f32_e32 vcc, s54, v96
	v_add_f32_e32 v55, v90, v55
	s_nop 0
	v_cndmask_b32_e32 v97, v242, v97, vcc
	v_mul_f32_e32 v55, v55, v97
	ds_write_b32 v98, v52 offset:35072
	ds_write_b32 v98, v53 offset:43264
	ds_write_b32 v99, v54 offset:2048
	ds_write_b32 v99, v55 offset:10240
	v_fmac_f32_e32 v65, v52, v52
	v_fmac_f32_e32 v65, v53, v53
	v_fmac_f32_e32 v64, v54, v54
	v_fmac_f32_e32 v64, v55, v55
	v_mov_b32_e32 v52, 0
	v_mov_b32_e32 v53, 0
	v_mov_b32_e32 v54, 0
	v_mov_b32_e32 v55, 0
	global_load_dwordx4 v[162:165], v[92:93], off
	global_load_dwordx4 v[166:169], v[92:93], off offset:256
	global_load_dwordx4 v[170:173], v[92:93], off offset:512
	global_load_dwordx4 v[174:177], v[92:93], off offset:768
	global_load_dwordx4 v[178:181], v[92:93], off offset:1024
	global_load_dwordx4 v[182:185], v[92:93], off offset:1280
	global_load_dwordx4 v[186:189], v[92:93], off offset:1536
	global_load_dwordx4 v[190:193], v[92:93], off offset:1792
	s_waitcnt vmcnt(16)
	ds_read_b128 v[44:47], v94 offset:64
	ds_read_b128 v[48:51], v94 offset:80
	ds_read_b128 v[152:155], v94 offset:96
	ds_read_b128 v[156:159], v94 offset:112
	s_waitcnt lgkmcnt(4)
	v_pk_fma_f32 v[52:53], v[0:1], v[136:137], v[52:53] op_sel_hi:[0,1,1]
	v_pk_fma_f32 v[54:55], v[0:1], v[138:139], v[54:55] op_sel_hi:[0,1,1]
	v_pk_fma_f32 v[52:53], v[0:1], v[140:141], v[52:53] op_sel:[1,0,0]
	v_pk_fma_f32 v[54:55], v[0:1], v[142:143], v[54:55] op_sel:[1,0,0]
	v_pk_fma_f32 v[52:53], v[2:3], v[144:145], v[52:53] op_sel_hi:[0,1,1]
	v_pk_fma_f32 v[54:55], v[2:3], v[146:147], v[54:55] op_sel_hi:[0,1,1]
	v_pk_fma_f32 v[52:53], v[2:3], v[148:149], v[52:53] op_sel:[1,0,0]
	v_pk_fma_f32 v[54:55], v[2:3], v[150:151], v[54:55] op_sel:[1,0,0]
	ds_read_b128 v[136:139], v94 offset:128
	ds_read_b128 v[140:143], v94 offset:144
	ds_read_b128 v[144:147], v94 offset:160
	ds_read_b128 v[148:151], v94 offset:176
	s_waitcnt lgkmcnt(4)
; __device__ __forceinline__ void hyena_task(const Params& p, int layer, int c, bool isctx, unsigned char* smem) {
;     ...
;         for (int q = 0; q < 16; q++) {
;           float4 hh = hp[q];
;           a0 += hh.x * misc[4 * q] + hh.y * misc[4 * q + 1] + hh.z * misc[4 * q + 2] + hh.w * misc[4 * q + 3];
;           a1 += hh.x * misc[64 + 4 * q] + hh.y * misc[64 + 4 * q + 1] + hh.z * misc[64 + 4 * q + 2] + hh.w * misc[64 + 4 * q + 3];
;           a2 += hh.x * misc[128 + 4 * q] + hh.y * misc[128 + 4 * q + 1] + hh.z * misc[128 + 4 * q + 2] + hh.w * misc[128 + 4 * q + 3];
;           a3 += hh.x * misc[192 + 4 * q] + hh.y * misc[192 + 4 * q + 1] + hh.z * misc[192 + 4 * q + 2] + hh.w * misc[192 + 4 * q + 3];
;         }
	v_pk_fma_f32 v[52:53], v[4:5], v[44:45], v[52:53] op_sel_hi:[0,1,1]
	v_pk_fma_f32 v[54:55], v[4:5], v[46:47], v[54:55] op_sel_hi:[0,1,1]
	v_pk_fma_f32 v[52:53], v[4:5], v[48:49], v[52:53] op_sel:[1,0,0]
	v_pk_fma_f32 v[54:55], v[4:5], v[50:51], v[54:55] op_sel:[1,0,0]
	v_pk_fma_f32 v[52:53], v[6:7], v[152:153], v[52:53] op_sel_hi:[0,1,1]
	v_pk_fma_f32 v[54:55], v[6:7], v[154:155], v[54:55] op_sel_hi:[0,1,1]
	v_pk_fma_f32 v[52:53], v[6:7], v[156:157], v[52:53] op_sel:[1,0,0]
	v_pk_fma_f32 v[54:55], v[6:7], v[158:159], v[54:55] op_sel:[1,0,0]
	ds_read_b128 v[44:47], v94 offset:192
	ds_read_b128 v[48:51], v94 offset:208
	ds_read_b128 v[152:155], v94 offset:224
	ds_read_b128 v[156:159], v94 offset:240
	s_waitcnt lgkmcnt(4)
	v_pk_fma_f32 v[52:53], v[8:9], v[136:137], v[52:53] op_sel_hi:[0,1,1]
	v_pk_fma_f32 v[54:55], v[8:9], v[138:139], v[54:55] op_sel_hi:[0,1,1]
	v_pk_fma_f32 v[52:53], v[8:9], v[140:141], v[52:53] op_sel:[1,0,0]
	v_pk_fma_f32 v[54:55], v[8:9], v[142:143], v[54:55] op_sel:[1,0,0]
	v_pk_fma_f32 v[52:53], v[10:11], v[144:145], v[52:53] op_sel_hi:[0,1,1]
	v_pk_fma_f32 v[54:55], v[10:11], v[146:147], v[54:55] op_sel_hi:[0,1,1]
	v_pk_fma_f32 v[52:53], v[10:11], v[148:149], v[52:53] op_sel:[1,0,0]
	v_pk_fma_f32 v[54:55], v[10:11], v[150:151], v[54:55] op_sel:[1,0,0]
	ds_read_b128 v[136:139], v94 offset:256
	ds_read_b128 v[140:143], v94 offset:272
	ds_read_b128 v[144:147], v94 offset:288
	ds_read_b128 v[148:151], v94 offset:304
	s_waitcnt lgkmcnt(4)
	v_pk_fma_f32 v[52:53], v[12:13], v[44:45], v[52:53] op_sel_hi:[0,1,1]
	v_pk_fma_f32 v[54:55], v[12:13], v[46:47], v[54:55] op_sel_hi:[0,1,1]
	v_pk_fma_f32 v[52:53], v[12:13], v[48:49], v[52:53] op_sel:[1,0,0]
	v_pk_fma_f32 v[54:55], v[12:13], v[50:51], v[54:55] op_sel:[1,0,0]
	v_pk_fma_f32 v[52:53], v[14:15], v[152:153], v[52:53] op_sel_hi:[0,1,1]
	v_pk_fma_f32 v[54:55], v[14:15], v[154:155], v[54:55] op_sel_hi:[0,1,1]
	v_pk_fma_f32 v[52:53], v[14:15], v[156:157], v[52:53] op_sel:[1,0,0]
	v_pk_fma_f32 v[54:55], v[14:15], v[158:159], v[54:55] op_sel:[1,0,0]
	ds_read_b128 v[44:47], v94 offset:320
	ds_read_b128 v[48:51], v94 offset:336
	ds_read_b128 v[152:155], v94 offset:352
	ds_read_b128 v[156:159], v94 offset:368
	s_waitcnt lgkmcnt(4)
	v_pk_fma_f32 v[52:53], v[16:17], v[136:137], v[52:53] op_sel_hi:[0,1,1]
	v_pk_fma_f32 v[54:55], v[16:17], v[138:139], v[54:55] op_sel_hi:[0,1,1]
	v_pk_fma_f32 v[52:53], v[16:17], v[140:141], v[52:53] op_sel:[1,0,0]
	v_pk_fma_f32 v[54:55], v[16:17], v[142:143], v[54:55] op_sel:[1,0,0]
	v_pk_fma_f32 v[52:53], v[18:19], v[144:145], v[52:53] op_sel_hi:[0,1,1]
	v_pk_fma_f32 v[54:55], v[18:19], v[146:147], v[54:55] op_sel_hi:[0,1,1]
	v_pk_fma_f32 v[52:53], v[18:19], v[148:149], v[52:53] op_sel:[1,0,0]
	v_pk_fma_f32 v[54:55], v[18:19], v[150:151], v[54:55] op_sel:[1,0,0]
	ds_read_b128 v[136:139], v94 offset:384
	ds_read_b128 v[140:143], v94 offset:400
	ds_read_b128 v[144:147], v94 offset:416
	ds_read_b128 v[148:151], v94 offset:432
	s_waitcnt lgkmcnt(4)
	v_pk_fma_f32 v[52:53], v[20:21], v[44:45], v[52:53] op_sel_hi:[0,1,1]
	v_pk_fma_f32 v[54:55], v[20:21], v[46:47], v[54:55] op_sel_hi:[0,1,1]
	v_pk_fma_f32 v[52:53], v[20:21], v[48:49], v[52:53] op_sel:[1,0,0]
	v_pk_fma_f32 v[54:55], v[20:21], v[50:51], v[54:55] op_sel:[1,0,0]
	v_pk_fma_f32 v[52:53], v[22:23], v[152:153], v[52:53] op_sel_hi:[0,1,1]
	v_pk_fma_f32 v[54:55], v[22:23], v[154:155], v[54:55] op_sel_hi:[0,1,1]
	v_pk_fma_f32 v[52:53], v[22:23], v[156:157], v[52:53] op_sel:[1,0,0]
	v_pk_fma_f32 v[54:55], v[22:23], v[158:159], v[54:55] op_sel:[1,0,0]
	ds_read_b128 v[44:47], v94 offset:448
	ds_read_b128 v[48:51], v94 offset:464
	ds_read_b128 v[152:155], v94 offset:480
	ds_read_b128 v[156:159], v94 offset:496
	s_waitcnt lgkmcnt(4)
	v_pk_fma_f32 v[52:53], v[24:25], v[136:137], v[52:53] op_sel_hi:[0,1,1]
	v_pk_fma_f32 v[54:55], v[24:25], v[138:139], v[54:55] op_sel_hi:[0,1,1]
	v_pk_fma_f32 v[52:53], v[24:25], v[140:141], v[52:53] op_sel:[1,0,0]
	v_pk_fma_f32 v[54:55], v[24:25], v[142:143], v[54:55] op_sel:[1,0,0]
	v_pk_fma_f32 v[52:53], v[26:27], v[144:145], v[52:53] op_sel_hi:[0,1,1]
	v_pk_fma_f32 v[54:55], v[26:27], v[146:147], v[54:55] op_sel_hi:[0,1,1]
	v_pk_fma_f32 v[52:53], v[26:27], v[148:149], v[52:53] op_sel:[1,0,0]
	v_pk_fma_f32 v[54:55], v[26:27], v[150:151], v[54:55] op_sel:[1,0,0]
	ds_read_b128 v[136:139], v94 offset:512
	ds_read_b128 v[140:143], v94 offset:528
	ds_read_b128 v[144:147], v94 offset:544
	ds_read_b128 v[148:151], v94 offset:560
	s_waitcnt lgkmcnt(4)
	v_pk_fma_f32 v[52:53], v[28:29], v[44:45], v[52:53] op_sel_hi:[0,1,1]
	v_pk_fma_f32 v[54:55], v[28:29], v[46:47], v[54:55] op_sel_hi:[0,1,1]
	v_pk_fma_f32 v[52:53], v[28:29], v[48:49], v[52:53] op_sel:[1,0,0]
	v_pk_fma_f32 v[54:55], v[28:29], v[50:51], v[54:55] op_sel:[1,0,0]
	v_pk_fma_f32 v[52:53], v[30:31], v[152:153], v[52:53] op_sel_hi:[0,1,1]
	v_pk_fma_f32 v[54:55], v[30:31], v[154:155], v[54:55] op_sel_hi:[0,1,1]
	v_pk_fma_f32 v[52:53], v[30:31], v[156:157], v[52:53] op_sel:[1,0,0]
	v_pk_fma_f32 v[54:55], v[30:31], v[158:159], v[54:55] op_sel:[1,0,0]
	global_load_dwordx4 v[0:3], v[92:93], off offset:2048
	global_load_dwordx4 v[4:7], v[92:93], off offset:2304
	global_load_dwordx4 v[8:11], v[92:93], off offset:2560
	global_load_dwordx4 v[12:15], v[92:93], off offset:2816
	global_load_dwordx4 v[16:19], v[92:93], off offset:3072
	global_load_dwordx4 v[20:23], v[92:93], off offset:3328
	global_load_dwordx4 v[24:27], v[92:93], off offset:3584
	global_load_dwordx4 v[28:31], v[92:93], off offset:3840
	v_lshl_add_u64 v[92:93], v[92:93], 0, s[4:5]
	s_waitcnt vmcnt(16)
; __device__ __forceinline__ void hyena_task(const Params& p, int layer, int c, bool isctx, unsigned char* smem) {
;     ...
;         for (int q = 0; q < 16; q++) {
;           float4 hh = hp[q];
;           a0 += hh.x * misc[4 * q] + hh.y * misc[4 * q + 1] + hh.z * misc[4 * q + 2] + hh.w * misc[4 * q + 3];
;           a1 += hh.x * misc[64 + 4 * q] + hh.y * misc[64 + 4 * q + 1] + hh.z * misc[64 + 4 * q + 2] + hh.w * misc[64 + 4 * q + 3];
;           a2 += hh.x * misc[128 + 4 * q] + hh.y * misc[128 + 4 * q + 1] + hh.z * misc[128 + 4 * q + 2] + hh.w * misc[128 + 4 * q + 3];
;           a3 += hh.x * misc[192 + 4 * q] + hh.y * misc[192 + 4 * q + 1] + hh.z * misc[192 + 4 * q + 2] + hh.w * misc[192 + 4 * q + 3];
;         }
	ds_read_b128 v[44:47], v94 offset:576
	ds_read_b128 v[48:51], v94 offset:592
	ds_read_b128 v[152:155], v94 offset:608
	ds_read_b128 v[156:159], v94 offset:624
	s_waitcnt lgkmcnt(4)
	v_pk_fma_f32 v[52:53], v[194:195], v[136:137], v[52:53] op_sel_hi:[0,1,1]
	v_pk_fma_f32 v[54:55], v[194:195], v[138:139], v[54:55] op_sel_hi:[0,1,1]
	v_pk_fma_f32 v[52:53], v[194:195], v[140:141], v[52:53] op_sel:[1,0,0]
	v_pk_fma_f32 v[54:55], v[194:195], v[142:143], v[54:55] op_sel:[1,0,0]
	v_pk_fma_f32 v[52:53], v[196:197], v[144:145], v[52:53] op_sel_hi:[0,1,1]
	v_pk_fma_f32 v[54:55], v[196:197], v[146:147], v[54:55] op_sel_hi:[0,1,1]
	v_pk_fma_f32 v[52:53], v[196:197], v[148:149], v[52:53] op_sel:[1,0,0]
	v_pk_fma_f32 v[54:55], v[196:197], v[150:151], v[54:55] op_sel:[1,0,0]
	ds_read_b128 v[136:139], v94 offset:640
	ds_read_b128 v[140:143], v94 offset:656
	ds_read_b128 v[144:147], v94 offset:672
	ds_read_b128 v[148:151], v94 offset:688
	s_waitcnt lgkmcnt(4)
	v_pk_fma_f32 v[52:53], v[198:199], v[44:45], v[52:53] op_sel_hi:[0,1,1]
	v_pk_fma_f32 v[54:55], v[198:199], v[46:47], v[54:55] op_sel_hi:[0,1,1]
	v_pk_fma_f32 v[52:53], v[198:199], v[48:49], v[52:53] op_sel:[1,0,0]
	v_pk_fma_f32 v[54:55], v[198:199], v[50:51], v[54:55] op_sel:[1,0,0]
	v_pk_fma_f32 v[52:53], v[200:201], v[152:153], v[52:53] op_sel_hi:[0,1,1]
	v_pk_fma_f32 v[54:55], v[200:201], v[154:155], v[54:55] op_sel_hi:[0,1,1]
	v_pk_fma_f32 v[52:53], v[200:201], v[156:157], v[52:53] op_sel:[1,0,0]
	v_pk_fma_f32 v[54:55], v[200:201], v[158:159], v[54:55] op_sel:[1,0,0]
	ds_read_b128 v[44:47], v94 offset:704
	ds_read_b128 v[48:51], v94 offset:720
	ds_read_b128 v[152:155], v94 offset:736
	ds_read_b128 v[156:159], v94 offset:752
	s_waitcnt lgkmcnt(4)
	v_pk_fma_f32 v[52:53], v[202:203], v[136:137], v[52:53] op_sel_hi:[0,1,1]
	v_pk_fma_f32 v[54:55], v[202:203], v[138:139], v[54:55] op_sel_hi:[0,1,1]
	v_pk_fma_f32 v[52:53], v[202:203], v[140:141], v[52:53] op_sel:[1,0,0]
	v_pk_fma_f32 v[54:55], v[202:203], v[142:143], v[54:55] op_sel:[1,0,0]
	v_pk_fma_f32 v[52:53], v[204:205], v[144:145], v[52:53] op_sel_hi:[0,1,1]
	v_pk_fma_f32 v[54:55], v[204:205], v[146:147], v[54:55] op_sel_hi:[0,1,1]
	v_pk_fma_f32 v[52:53], v[204:205], v[148:149], v[52:53] op_sel:[1,0,0]
	v_pk_fma_f32 v[54:55], v[204:205], v[150:151], v[54:55] op_sel:[1,0,0]
	ds_read_b128 v[136:139], v94 offset:768
	ds_read_b128 v[140:143], v94 offset:784
	ds_read_b128 v[144:147], v94 offset:800
	ds_read_b128 v[148:151], v94 offset:816
	s_waitcnt lgkmcnt(4)
	v_pk_fma_f32 v[52:53], v[206:207], v[44:45], v[52:53] op_sel_hi:[0,1,1]
	v_pk_fma_f32 v[54:55], v[206:207], v[46:47], v[54:55] op_sel_hi:[0,1,1]
	v_pk_fma_f32 v[52:53], v[206:207], v[48:49], v[52:53] op_sel:[1,0,0]
	v_pk_fma_f32 v[54:55], v[206:207], v[50:51], v[54:55] op_sel:[1,0,0]
	v_pk_fma_f32 v[52:53], v[208:209], v[152:153], v[52:53] op_sel_hi:[0,1,1]
	v_pk_fma_f32 v[54:55], v[208:209], v[154:155], v[54:55] op_sel_hi:[0,1,1]
	v_pk_fma_f32 v[52:53], v[208:209], v[156:157], v[52:53] op_sel:[1,0,0]
	v_pk_fma_f32 v[54:55], v[208:209], v[158:159], v[54:55] op_sel:[1,0,0]
	ds_read_b128 v[44:47], v94 offset:832
	ds_read_b128 v[48:51], v94 offset:848
	ds_read_b128 v[152:155], v94 offset:864
	ds_read_b128 v[156:159], v94 offset:880
	s_waitcnt lgkmcnt(4)
	v_pk_fma_f32 v[52:53], v[210:211], v[136:137], v[52:53] op_sel_hi:[0,1,1]
	v_pk_fma_f32 v[54:55], v[210:211], v[138:139], v[54:55] op_sel_hi:[0,1,1]
	v_pk_fma_f32 v[52:53], v[210:211], v[140:141], v[52:53] op_sel:[1,0,0]
	v_pk_fma_f32 v[54:55], v[210:211], v[142:143], v[54:55] op_sel:[1,0,0]
	v_pk_fma_f32 v[52:53], v[212:213], v[144:145], v[52:53] op_sel_hi:[0,1,1]
	v_pk_fma_f32 v[54:55], v[212:213], v[146:147], v[54:55] op_sel_hi:[0,1,1]
	v_pk_fma_f32 v[52:53], v[212:213], v[148:149], v[52:53] op_sel:[1,0,0]
	v_pk_fma_f32 v[54:55], v[212:213], v[150:151], v[54:55] op_sel:[1,0,0]
	ds_read_b128 v[136:139], v94 offset:896
	ds_read_b128 v[140:143], v94 offset:912
	ds_read_b128 v[144:147], v94 offset:928
	ds_read_b128 v[148:151], v94 offset:944
	s_waitcnt lgkmcnt(4)
	v_pk_fma_f32 v[52:53], v[32:33], v[44:45], v[52:53] op_sel_hi:[0,1,1]
	v_pk_fma_f32 v[54:55], v[32:33], v[46:47], v[54:55] op_sel_hi:[0,1,1]
	v_pk_fma_f32 v[52:53], v[32:33], v[48:49], v[52:53] op_sel:[1,0,0]
	v_pk_fma_f32 v[54:55], v[32:33], v[50:51], v[54:55] op_sel:[1,0,0]
	v_pk_fma_f32 v[52:53], v[34:35], v[152:153], v[52:53] op_sel_hi:[0,1,1]
	v_pk_fma_f32 v[54:55], v[34:35], v[154:155], v[54:55] op_sel_hi:[0,1,1]
	v_pk_fma_f32 v[52:53], v[34:35], v[156:157], v[52:53] op_sel:[1,0,0]
	v_pk_fma_f32 v[54:55], v[34:35], v[158:159], v[54:55] op_sel:[1,0,0]
	ds_read_b128 v[44:47], v94 offset:960
	ds_read_b128 v[48:51], v94 offset:976
	ds_read_b128 v[152:155], v94 offset:992
	ds_read_b128 v[156:159], v94 offset:1008
	s_waitcnt lgkmcnt(4)
	v_pk_fma_f32 v[52:53], v[36:37], v[136:137], v[52:53] op_sel_hi:[0,1,1]
	v_pk_fma_f32 v[54:55], v[36:37], v[138:139], v[54:55] op_sel_hi:[0,1,1]
	v_pk_fma_f32 v[52:53], v[36:37], v[140:141], v[52:53] op_sel:[1,0,0]
	v_pk_fma_f32 v[54:55], v[36:37], v[142:143], v[54:55] op_sel:[1,0,0]
	v_pk_fma_f32 v[52:53], v[38:39], v[144:145], v[52:53] op_sel_hi:[0,1,1]
	v_pk_fma_f32 v[54:55], v[38:39], v[146:147], v[54:55] op_sel_hi:[0,1,1]
	v_pk_fma_f32 v[52:53], v[38:39], v[148:149], v[52:53] op_sel:[1,0,0]
	v_pk_fma_f32 v[54:55], v[38:39], v[150:151], v[54:55] op_sel:[1,0,0]
	ds_read_b128 v[136:139], v94
	ds_read_b128 v[140:143], v94 offset:16
	ds_read_b128 v[144:147], v94 offset:32
	ds_read_b128 v[148:151], v94 offset:48
	s_waitcnt lgkmcnt(4)
; __device__ __forceinline__ void hyena_task(const Params& p, int layer, int c, bool isctx, unsigned char* smem) {
;     ...
;         for (int q = 0; q < 16; q++) {
;           float4 hh = hp[q];
;           a0 += hh.x * misc[4 * q] + hh.y * misc[4 * q + 1] + hh.z * misc[4 * q + 2] + hh.w * misc[4 * q + 3];
;           a1 += hh.x * misc[64 + 4 * q] + hh.y * misc[64 + 4 * q + 1] + hh.z * misc[64 + 4 * q + 2] + hh.w * misc[64 + 4 * q + 3];
;           a2 += hh.x * misc[128 + 4 * q] + hh.y * misc[128 + 4 * q + 1] + hh.z * misc[128 + 4 * q + 2] + hh.w * misc[128 + 4 * q + 3];
;           a3 += hh.x * misc[192 + 4 * q] + hh.y * misc[192 + 4 * q + 1] + hh.z * misc[192 + 4 * q + 2] + hh.w * misc[192 + 4 * q + 3];
;         }
;         float tn = (float)t / (float)Ls;
;         float v0 = (a0 + b3[0]) * expf(-tn * dc[0]), v1 = (a1 + b3[1]) * expf(-tn * dc[1]);
;         float v2 = (a2 + b3[2]) * expf(-tn * dc[2]), v3 = (a3 + b3[3]) * expf(-tn * dc[3]);
;         tmp[t] = v0; tmp[2048 + t] = v1; tmp1[t] = v2; tmp1[2048 + t] = v3;
;         ssq0 += v0 * v0 + v1 * v1; ssq1 += v2 * v2 + v3 * v3;
	v_pk_fma_f32 v[52:53], v[40:41], v[44:45], v[52:53] op_sel_hi:[0,1,1]
	v_pk_fma_f32 v[54:55], v[40:41], v[46:47], v[54:55] op_sel_hi:[0,1,1]
	v_pk_fma_f32 v[52:53], v[40:41], v[48:49], v[52:53] op_sel:[1,0,0]
	v_pk_fma_f32 v[54:55], v[40:41], v[50:51], v[54:55] op_sel:[1,0,0]
	v_pk_fma_f32 v[52:53], v[42:43], v[152:153], v[52:53] op_sel_hi:[0,1,1]
	v_pk_fma_f32 v[54:55], v[42:43], v[154:155], v[54:55] op_sel_hi:[0,1,1]
	v_pk_fma_f32 v[52:53], v[42:43], v[156:157], v[52:53] op_sel:[1,0,0]
	v_pk_fma_f32 v[54:55], v[42:43], v[158:159], v[54:55] op_sel:[1,0,0]
	v_add_u32_e32 v100, 0x400, v66
	v_cvt_f32_i32_e32 v100, v100
	v_mul_f32_e32 v95, 0xba000000, v100
	v_mul_f32_e32 v96, v131, v95
	v_mul_f32_e32 v97, 0x3fb8aa3b, v96
	v_fma_f32 v100, v96, s55, -v97
	v_rndne_f32_e32 v101, v97
	v_fmac_f32_e32 v100, 0x32a5705f, v96
	v_sub_f32_e32 v97, v97, v101
	v_add_f32_e32 v97, v97, v100
	v_exp_f32_e32 v97, v97
	v_cvt_i32_f32_e32 v101, v101
	v_cmp_ngt_f32_e32 vcc, s56, v96
	v_ldexp_f32 v97, v97, v101
	s_nop 0
	v_cndmask_b32_e32 v97, 0, v97, vcc
	v_cmp_nlt_f32_e32 vcc, s54, v96
	v_add_f32_e32 v52, v89, v52
	s_nop 0
	v_cndmask_b32_e32 v97, v242, v97, vcc
	v_mul_f32_e32 v52, v52, v97
	v_mul_f32_e32 v96, v132, v95
	v_mul_f32_e32 v97, 0x3fb8aa3b, v96
	v_fma_f32 v100, v96, s55, -v97
	v_rndne_f32_e32 v101, v97
	v_fmac_f32_e32 v100, 0x32a5705f, v96
	v_sub_f32_e32 v97, v97, v101
	v_add_f32_e32 v97, v97, v100
	v_exp_f32_e32 v97, v97
	v_cvt_i32_f32_e32 v101, v101
	v_cmp_ngt_f32_e32 vcc, s56, v96
	v_ldexp_f32 v97, v97, v101
	s_nop 0
	v_cndmask_b32_e32 v97, 0, v97, vcc
	v_cmp_nlt_f32_e32 vcc, s54, v96
	v_add_f32_e32 v53, v91, v53
	s_nop 0
	v_cndmask_b32_e32 v97, v242, v97, vcc
	v_mul_f32_e32 v53, v53, v97
	v_mul_f32_e32 v96, v133, v95
	v_mul_f32_e32 v97, 0x3fb8aa3b, v96
	v_fma_f32 v100, v96, s55, -v97
	v_rndne_f32_e32 v101, v97
	v_fmac_f32_e32 v100, 0x32a5705f, v96
	v_sub_f32_e32 v97, v97, v101
	v_add_f32_e32 v97, v97, v100
	v_exp_f32_e32 v97, v97
	v_cvt_i32_f32_e32 v101, v101
	v_cmp_ngt_f32_e32 vcc, s56, v96
	v_ldexp_f32 v97, v97, v101
	s_nop 0
	v_cndmask_b32_e32 v97, 0, v97, vcc
	v_cmp_nlt_f32_e32 vcc, s54, v96
	v_add_f32_e32 v54, v88, v54
	s_nop 0
	v_cndmask_b32_e32 v97, v242, v97, vcc
	v_mul_f32_e32 v54, v54, v97
	v_mul_f32_e32 v96, v134, v95
	v_mul_f32_e32 v97, 0x3fb8aa3b, v96
	v_fma_f32 v100, v96, s55, -v97
	v_rndne_f32_e32 v101, v97
	v_fmac_f32_e32 v100, 0x32a5705f, v96
	v_sub_f32_e32 v97, v97, v101
	v_add_f32_e32 v97, v97, v100
	v_exp_f32_e32 v97, v97
	v_cvt_i32_f32_e32 v101, v101
	v_cmp_ngt_f32_e32 vcc, s56, v96
	v_ldexp_f32 v97, v97, v101
	s_nop 0
	v_cndmask_b32_e32 v97, 0, v97, vcc
	v_cmp_nlt_f32_e32 vcc, s54, v96
	v_add_f32_e32 v55, v90, v55
	s_nop 0
	v_cndmask_b32_e32 v97, v242, v97, vcc
	v_mul_f32_e32 v55, v55, v97
	ds_write_b32 v98, v52 offset:37120
	ds_write_b32 v98, v53 offset:45312
	ds_write_b32 v99, v54 offset:4096
	ds_write_b32 v99, v55 offset:12288
	v_fmac_f32_e32 v65, v52, v52
	v_fmac_f32_e32 v65, v53, v53
	v_fmac_f32_e32 v64, v54, v54
	v_fmac_f32_e32 v64, v55, v55
	v_mov_b32_e32 v52, 0
	v_mov_b32_e32 v53, 0
	v_mov_b32_e32 v54, 0
	v_mov_b32_e32 v55, 0
	s_waitcnt vmcnt(8)
	ds_read_b128 v[44:47], v94 offset:64
	ds_read_b128 v[48:51], v94 offset:80
	ds_read_b128 v[152:155], v94 offset:96
	ds_read_b128 v[156:159], v94 offset:112
	s_waitcnt lgkmcnt(4)
	v_pk_fma_f32 v[52:53], v[162:163], v[136:137], v[52:53] op_sel_hi:[0,1,1]
	v_pk_fma_f32 v[54:55], v[162:163], v[138:139], v[54:55] op_sel_hi:[0,1,1]
	v_pk_fma_f32 v[52:53], v[162:163], v[140:141], v[52:53] op_sel:[1,0,0]
	v_pk_fma_f32 v[54:55], v[162:163], v[142:143], v[54:55] op_sel:[1,0,0]
	v_pk_fma_f32 v[52:53], v[164:165], v[144:145], v[52:53] op_sel_hi:[0,1,1]
	v_pk_fma_f32 v[54:55], v[164:165], v[146:147], v[54:55] op_sel_hi:[0,1,1]
	v_pk_fma_f32 v[52:53], v[164:165], v[148:149], v[52:53] op_sel:[1,0,0]
	v_pk_fma_f32 v[54:55], v[164:165], v[150:151], v[54:55] op_sel:[1,0,0]
	ds_read_b128 v[136:139], v94 offset:128
	ds_read_b128 v[140:143], v94 offset:144
	ds_read_b128 v[144:147], v94 offset:160
	ds_read_b128 v[148:151], v94 offset:176
	s_waitcnt lgkmcnt(4)
	v_pk_fma_f32 v[52:53], v[166:167], v[44:45], v[52:53] op_sel_hi:[0,1,1]
	v_pk_fma_f32 v[54:55], v[166:167], v[46:47], v[54:55] op_sel_hi:[0,1,1]
	v_pk_fma_f32 v[52:53], v[166:167], v[48:49], v[52:53] op_sel:[1,0,0]
	v_pk_fma_f32 v[54:55], v[166:167], v[50:51], v[54:55] op_sel:[1,0,0]
	v_pk_fma_f32 v[52:53], v[168:169], v[152:153], v[52:53] op_sel_hi:[0,1,1]
	v_pk_fma_f32 v[54:55], v[168:169], v[154:155], v[54:55] op_sel_hi:[0,1,1]
	v_pk_fma_f32 v[52:53], v[168:169], v[156:157], v[52:53] op_sel:[1,0,0]
	v_pk_fma_f32 v[54:55], v[168:169], v[158:159], v[54:55] op_sel:[1,0,0]
	ds_read_b128 v[44:47], v94 offset:192
	ds_read_b128 v[48:51], v94 offset:208
	ds_read_b128 v[152:155], v94 offset:224
	ds_read_b128 v[156:159], v94 offset:240
	s_waitcnt lgkmcnt(4)
	v_pk_fma_f32 v[52:53], v[170:171], v[136:137], v[52:53] op_sel_hi:[0,1,1]
	v_pk_fma_f32 v[54:55], v[170:171], v[138:139], v[54:55] op_sel_hi:[0,1,1]
	v_pk_fma_f32 v[52:53], v[170:171], v[140:141], v[52:53] op_sel:[1,0,0]
	v_pk_fma_f32 v[54:55], v[170:171], v[142:143], v[54:55] op_sel:[1,0,0]
	v_pk_fma_f32 v[52:53], v[172:173], v[144:145], v[52:53] op_sel_hi:[0,1,1]
	v_pk_fma_f32 v[54:55], v[172:173], v[146:147], v[54:55] op_sel_hi:[0,1,1]
	v_pk_fma_f32 v[52:53], v[172:173], v[148:149], v[52:53] op_sel:[1,0,0]
	v_pk_fma_f32 v[54:55], v[172:173], v[150:151], v[54:55] op_sel:[1,0,0]
	ds_read_b128 v[136:139], v94 offset:256
	ds_read_b128 v[140:143], v94 offset:272
	ds_read_b128 v[144:147], v94 offset:288
	ds_read_b128 v[148:151], v94 offset:304
	s_waitcnt lgkmcnt(4)
; __device__ __forceinline__ void hyena_task(const Params& p, int layer, int c, bool isctx, unsigned char* smem) {
;     ...
;         for (int q = 0; q < 16; q++) {
;           float4 hh = hp[q];
;           a0 += hh.x * misc[4 * q] + hh.y * misc[4 * q + 1] + hh.z * misc[4 * q + 2] + hh.w * misc[4 * q + 3];
;           a1 += hh.x * misc[64 + 4 * q] + hh.y * misc[64 + 4 * q + 1] + hh.z * misc[64 + 4 * q + 2] + hh.w * misc[64 + 4 * q + 3];
;           a2 += hh.x * misc[128 + 4 * q] + hh.y * misc[128 + 4 * q + 1] + hh.z * misc[128 + 4 * q + 2] + hh.w * misc[128 + 4 * q + 3];
;           a3 += hh.x * misc[192 + 4 * q] + hh.y * misc[192 + 4 * q + 1] + hh.z * misc[192 + 4 * q + 2] + hh.w * misc[192 + 4 * q + 3];
;         }
	v_pk_fma_f32 v[52:53], v[174:175], v[44:45], v[52:53] op_sel_hi:[0,1,1]
	v_pk_fma_f32 v[54:55], v[174:175], v[46:47], v[54:55] op_sel_hi:[0,1,1]
	v_pk_fma_f32 v[52:53], v[174:175], v[48:49], v[52:53] op_sel:[1,0,0]
	v_pk_fma_f32 v[54:55], v[174:175], v[50:51], v[54:55] op_sel:[1,0,0]
	v_pk_fma_f32 v[52:53], v[176:177], v[152:153], v[52:53] op_sel_hi:[0,1,1]
	v_pk_fma_f32 v[54:55], v[176:177], v[154:155], v[54:55] op_sel_hi:[0,1,1]
	v_pk_fma_f32 v[52:53], v[176:177], v[156:157], v[52:53] op_sel:[1,0,0]
	v_pk_fma_f32 v[54:55], v[176:177], v[158:159], v[54:55] op_sel:[1,0,0]
	ds_read_b128 v[44:47], v94 offset:320
	ds_read_b128 v[48:51], v94 offset:336
	ds_read_b128 v[152:155], v94 offset:352
	ds_read_b128 v[156:159], v94 offset:368
	s_waitcnt lgkmcnt(4)
	v_pk_fma_f32 v[52:53], v[178:179], v[136:137], v[52:53] op_sel_hi:[0,1,1]
	v_pk_fma_f32 v[54:55], v[178:179], v[138:139], v[54:55] op_sel_hi:[0,1,1]
	v_pk_fma_f32 v[52:53], v[178:179], v[140:141], v[52:53] op_sel:[1,0,0]
	v_pk_fma_f32 v[54:55], v[178:179], v[142:143], v[54:55] op_sel:[1,0,0]
	v_pk_fma_f32 v[52:53], v[180:181], v[144:145], v[52:53] op_sel_hi:[0,1,1]
	v_pk_fma_f32 v[54:55], v[180:181], v[146:147], v[54:55] op_sel_hi:[0,1,1]
	v_pk_fma_f32 v[52:53], v[180:181], v[148:149], v[52:53] op_sel:[1,0,0]
	v_pk_fma_f32 v[54:55], v[180:181], v[150:151], v[54:55] op_sel:[1,0,0]
	ds_read_b128 v[136:139], v94 offset:384
	ds_read_b128 v[140:143], v94 offset:400
	ds_read_b128 v[144:147], v94 offset:416
	ds_read_b128 v[148:151], v94 offset:432
	s_waitcnt lgkmcnt(4)
	v_pk_fma_f32 v[52:53], v[182:183], v[44:45], v[52:53] op_sel_hi:[0,1,1]
	v_pk_fma_f32 v[54:55], v[182:183], v[46:47], v[54:55] op_sel_hi:[0,1,1]
	v_pk_fma_f32 v[52:53], v[182:183], v[48:49], v[52:53] op_sel:[1,0,0]
	v_pk_fma_f32 v[54:55], v[182:183], v[50:51], v[54:55] op_sel:[1,0,0]
	v_pk_fma_f32 v[52:53], v[184:185], v[152:153], v[52:53] op_sel_hi:[0,1,1]
	v_pk_fma_f32 v[54:55], v[184:185], v[154:155], v[54:55] op_sel_hi:[0,1,1]
	v_pk_fma_f32 v[52:53], v[184:185], v[156:157], v[52:53] op_sel:[1,0,0]
	v_pk_fma_f32 v[54:55], v[184:185], v[158:159], v[54:55] op_sel:[1,0,0]
	ds_read_b128 v[44:47], v94 offset:448
	ds_read_b128 v[48:51], v94 offset:464
	ds_read_b128 v[152:155], v94 offset:480
	ds_read_b128 v[156:159], v94 offset:496
	s_waitcnt lgkmcnt(4)
	v_pk_fma_f32 v[52:53], v[186:187], v[136:137], v[52:53] op_sel_hi:[0,1,1]
	v_pk_fma_f32 v[54:55], v[186:187], v[138:139], v[54:55] op_sel_hi:[0,1,1]
	v_pk_fma_f32 v[52:53], v[186:187], v[140:141], v[52:53] op_sel:[1,0,0]
	v_pk_fma_f32 v[54:55], v[186:187], v[142:143], v[54:55] op_sel:[1,0,0]
	v_pk_fma_f32 v[52:53], v[188:189], v[144:145], v[52:53] op_sel_hi:[0,1,1]
	v_pk_fma_f32 v[54:55], v[188:189], v[146:147], v[54:55] op_sel_hi:[0,1,1]
	v_pk_fma_f32 v[52:53], v[188:189], v[148:149], v[52:53] op_sel:[1,0,0]
	v_pk_fma_f32 v[54:55], v[188:189], v[150:151], v[54:55] op_sel:[1,0,0]
	ds_read_b128 v[136:139], v94 offset:512
	ds_read_b128 v[140:143], v94 offset:528
	ds_read_b128 v[144:147], v94 offset:544
	ds_read_b128 v[148:151], v94 offset:560
	s_waitcnt lgkmcnt(4)
	v_pk_fma_f32 v[52:53], v[190:191], v[44:45], v[52:53] op_sel_hi:[0,1,1]
	v_pk_fma_f32 v[54:55], v[190:191], v[46:47], v[54:55] op_sel_hi:[0,1,1]
	v_pk_fma_f32 v[52:53], v[190:191], v[48:49], v[52:53] op_sel:[1,0,0]
	v_pk_fma_f32 v[54:55], v[190:191], v[50:51], v[54:55] op_sel:[1,0,0]
	v_pk_fma_f32 v[52:53], v[192:193], v[152:153], v[52:53] op_sel_hi:[0,1,1]
	v_pk_fma_f32 v[54:55], v[192:193], v[154:155], v[54:55] op_sel_hi:[0,1,1]
	v_pk_fma_f32 v[52:53], v[192:193], v[156:157], v[52:53] op_sel:[1,0,0]
	v_pk_fma_f32 v[54:55], v[192:193], v[158:159], v[54:55] op_sel:[1,0,0]
	s_waitcnt vmcnt(0)
	ds_read_b128 v[44:47], v94 offset:576
	ds_read_b128 v[48:51], v94 offset:592
	ds_read_b128 v[152:155], v94 offset:608
	ds_read_b128 v[156:159], v94 offset:624
	s_waitcnt lgkmcnt(4)
	v_pk_fma_f32 v[52:53], v[0:1], v[136:137], v[52:53] op_sel_hi:[0,1,1]
	v_pk_fma_f32 v[54:55], v[0:1], v[138:139], v[54:55] op_sel_hi:[0,1,1]
	v_pk_fma_f32 v[52:53], v[0:1], v[140:141], v[52:53] op_sel:[1,0,0]
	v_pk_fma_f32 v[54:55], v[0:1], v[142:143], v[54:55] op_sel:[1,0,0]
	v_pk_fma_f32 v[52:53], v[2:3], v[144:145], v[52:53] op_sel_hi:[0,1,1]
	v_pk_fma_f32 v[54:55], v[2:3], v[146:147], v[54:55] op_sel_hi:[0,1,1]
	v_pk_fma_f32 v[52:53], v[2:3], v[148:149], v[52:53] op_sel:[1,0,0]
	v_pk_fma_f32 v[54:55], v[2:3], v[150:151], v[54:55] op_sel:[1,0,0]
	ds_read_b128 v[136:139], v94 offset:640
	ds_read_b128 v[140:143], v94 offset:656
	ds_read_b128 v[144:147], v94 offset:672
	ds_read_b128 v[148:151], v94 offset:688
	s_waitcnt lgkmcnt(4)
	v_pk_fma_f32 v[52:53], v[4:5], v[44:45], v[52:53] op_sel_hi:[0,1,1]
	v_pk_fma_f32 v[54:55], v[4:5], v[46:47], v[54:55] op_sel_hi:[0,1,1]
	v_pk_fma_f32 v[52:53], v[4:5], v[48:49], v[52:53] op_sel:[1,0,0]
	v_pk_fma_f32 v[54:55], v[4:5], v[50:51], v[54:55] op_sel:[1,0,0]
	v_pk_fma_f32 v[52:53], v[6:7], v[152:153], v[52:53] op_sel_hi:[0,1,1]
	v_pk_fma_f32 v[54:55], v[6:7], v[154:155], v[54:55] op_sel_hi:[0,1,1]
	v_pk_fma_f32 v[52:53], v[6:7], v[156:157], v[52:53] op_sel:[1,0,0]
	v_pk_fma_f32 v[54:55], v[6:7], v[158:159], v[54:55] op_sel:[1,0,0]
	ds_read_b128 v[44:47], v94 offset:704
	ds_read_b128 v[48:51], v94 offset:720
	ds_read_b128 v[152:155], v94 offset:736
	ds_read_b128 v[156:159], v94 offset:752
	s_waitcnt lgkmcnt(4)
; __device__ __forceinline__ void hyena_task(const Params& p, int layer, int c, bool isctx, unsigned char* smem) {
;     ...
;         for (int q = 0; q < 16; q++) {
;           float4 hh = hp[q];
;           a0 += hh.x * misc[4 * q] + hh.y * misc[4 * q + 1] + hh.z * misc[4 * q + 2] + hh.w * misc[4 * q + 3];
;           a1 += hh.x * misc[64 + 4 * q] + hh.y * misc[64 + 4 * q + 1] + hh.z * misc[64 + 4 * q + 2] + hh.w * misc[64 + 4 * q + 3];
;           a2 += hh.x * misc[128 + 4 * q] + hh.y * misc[128 + 4 * q + 1] + hh.z * misc[128 + 4 * q + 2] + hh.w * misc[128 + 4 * q + 3];
;           a3 += hh.x * misc[192 + 4 * q] + hh.y * misc[192 + 4 * q + 1] + hh.z * misc[192 + 4 * q + 2] + hh.w * misc[192 + 4 * q + 3];
;         }
;         float tn = (float)t / (float)Ls;
;         float v0 = (a0 + b3[0]) * expf(-tn * dc[0]), v1 = (a1 + b3[1]) * expf(-tn * dc[1]);
;         float v2 = (a2 + b3[2]) * expf(-tn * dc[2]), v3 = (a3 + b3[3]) * expf(-tn * dc[3]);
;         tmp[t] = v0; tmp[2048 + t] = v1; tmp1[t] = v2; tmp1[2048 + t] = v3;
;         ssq0 += v0 * v0 + v1 * v1; ssq1 += v2 * v2 + v3 * v3;
;       }
;       ssq0 = wave_sum(ssq0); ssq1 = wave_sum(ssq1);
;       if (lane == 0) { misc[256 + wave] = ssq0; misc[264 + wave] = ssq1; }
	v_pk_fma_f32 v[52:53], v[8:9], v[136:137], v[52:53] op_sel_hi:[0,1,1]
	v_pk_fma_f32 v[54:55], v[8:9], v[138:139], v[54:55] op_sel_hi:[0,1,1]
	v_pk_fma_f32 v[52:53], v[8:9], v[140:141], v[52:53] op_sel:[1,0,0]
	v_pk_fma_f32 v[54:55], v[8:9], v[142:143], v[54:55] op_sel:[1,0,0]
	v_pk_fma_f32 v[52:53], v[10:11], v[144:145], v[52:53] op_sel_hi:[0,1,1]
	v_pk_fma_f32 v[54:55], v[10:11], v[146:147], v[54:55] op_sel_hi:[0,1,1]
	v_pk_fma_f32 v[52:53], v[10:11], v[148:149], v[52:53] op_sel:[1,0,0]
	v_pk_fma_f32 v[54:55], v[10:11], v[150:151], v[54:55] op_sel:[1,0,0]
	ds_read_b128 v[136:139], v94 offset:768
	ds_read_b128 v[140:143], v94 offset:784
	ds_read_b128 v[144:147], v94 offset:800
	ds_read_b128 v[148:151], v94 offset:816
	s_waitcnt lgkmcnt(4)
	v_pk_fma_f32 v[52:53], v[12:13], v[44:45], v[52:53] op_sel_hi:[0,1,1]
	v_pk_fma_f32 v[54:55], v[12:13], v[46:47], v[54:55] op_sel_hi:[0,1,1]
	v_pk_fma_f32 v[52:53], v[12:13], v[48:49], v[52:53] op_sel:[1,0,0]
	v_pk_fma_f32 v[54:55], v[12:13], v[50:51], v[54:55] op_sel:[1,0,0]
	v_pk_fma_f32 v[52:53], v[14:15], v[152:153], v[52:53] op_sel_hi:[0,1,1]
	v_pk_fma_f32 v[54:55], v[14:15], v[154:155], v[54:55] op_sel_hi:[0,1,1]
	v_pk_fma_f32 v[52:53], v[14:15], v[156:157], v[52:53] op_sel:[1,0,0]
	v_pk_fma_f32 v[54:55], v[14:15], v[158:159], v[54:55] op_sel:[1,0,0]
	ds_read_b128 v[44:47], v94 offset:832
	ds_read_b128 v[48:51], v94 offset:848
	ds_read_b128 v[152:155], v94 offset:864
	ds_read_b128 v[156:159], v94 offset:880
	s_waitcnt lgkmcnt(4)
	v_pk_fma_f32 v[52:53], v[16:17], v[136:137], v[52:53] op_sel_hi:[0,1,1]
	v_pk_fma_f32 v[54:55], v[16:17], v[138:139], v[54:55] op_sel_hi:[0,1,1]
	v_pk_fma_f32 v[52:53], v[16:17], v[140:141], v[52:53] op_sel:[1,0,0]
	v_pk_fma_f32 v[54:55], v[16:17], v[142:143], v[54:55] op_sel:[1,0,0]
	v_pk_fma_f32 v[52:53], v[18:19], v[144:145], v[52:53] op_sel_hi:[0,1,1]
	v_pk_fma_f32 v[54:55], v[18:19], v[146:147], v[54:55] op_sel_hi:[0,1,1]
	v_pk_fma_f32 v[52:53], v[18:19], v[148:149], v[52:53] op_sel:[1,0,0]
	v_pk_fma_f32 v[54:55], v[18:19], v[150:151], v[54:55] op_sel:[1,0,0]
	ds_read_b128 v[136:139], v94 offset:896
	ds_read_b128 v[140:143], v94 offset:912
	ds_read_b128 v[144:147], v94 offset:928
	ds_read_b128 v[148:151], v94 offset:944
	s_waitcnt lgkmcnt(4)
	v_pk_fma_f32 v[52:53], v[20:21], v[44:45], v[52:53] op_sel_hi:[0,1,1]
	v_pk_fma_f32 v[54:55], v[20:21], v[46:47], v[54:55] op_sel_hi:[0,1,1]
	v_pk_fma_f32 v[52:53], v[20:21], v[48:49], v[52:53] op_sel:[1,0,0]
	v_pk_fma_f32 v[54:55], v[20:21], v[50:51], v[54:55] op_sel:[1,0,0]
	v_pk_fma_f32 v[52:53], v[22:23], v[152:153], v[52:53] op_sel_hi:[0,1,1]
	v_pk_fma_f32 v[54:55], v[22:23], v[154:155], v[54:55] op_sel_hi:[0,1,1]
	v_pk_fma_f32 v[52:53], v[22:23], v[156:157], v[52:53] op_sel:[1,0,0]
	v_pk_fma_f32 v[54:55], v[22:23], v[158:159], v[54:55] op_sel:[1,0,0]
	ds_read_b128 v[44:47], v94 offset:960
	ds_read_b128 v[48:51], v94 offset:976
	ds_read_b128 v[152:155], v94 offset:992
	ds_read_b128 v[156:159], v94 offset:1008
	s_waitcnt lgkmcnt(4)
	v_pk_fma_f32 v[52:53], v[24:25], v[136:137], v[52:53] op_sel_hi:[0,1,1]
	v_pk_fma_f32 v[54:55], v[24:25], v[138:139], v[54:55] op_sel_hi:[0,1,1]
	v_pk_fma_f32 v[52:53], v[24:25], v[140:141], v[52:53] op_sel:[1,0,0]
	v_pk_fma_f32 v[54:55], v[24:25], v[142:143], v[54:55] op_sel:[1,0,0]
	v_pk_fma_f32 v[52:53], v[26:27], v[144:145], v[52:53] op_sel_hi:[0,1,1]
	v_pk_fma_f32 v[54:55], v[26:27], v[146:147], v[54:55] op_sel_hi:[0,1,1]
	v_pk_fma_f32 v[52:53], v[26:27], v[148:149], v[52:53] op_sel:[1,0,0]
	v_pk_fma_f32 v[54:55], v[26:27], v[150:151], v[54:55] op_sel:[1,0,0]
	s_waitcnt lgkmcnt(0)
	v_pk_fma_f32 v[52:53], v[28:29], v[44:45], v[52:53] op_sel_hi:[0,1,1]
	v_pk_fma_f32 v[54:55], v[28:29], v[46:47], v[54:55] op_sel_hi:[0,1,1]
	v_pk_fma_f32 v[52:53], v[28:29], v[48:49], v[52:53] op_sel:[1,0,0]
	v_pk_fma_f32 v[54:55], v[28:29], v[50:51], v[54:55] op_sel:[1,0,0]
	v_pk_fma_f32 v[52:53], v[30:31], v[152:153], v[52:53] op_sel_hi:[0,1,1]
	v_pk_fma_f32 v[54:55], v[30:31], v[154:155], v[54:55] op_sel_hi:[0,1,1]
	v_pk_fma_f32 v[52:53], v[30:31], v[156:157], v[52:53] op_sel:[1,0,0]
	v_pk_fma_f32 v[54:55], v[30:31], v[158:159], v[54:55] op_sel:[1,0,0]
	v_add_u32_e32 v100, 0x600, v66
	v_cvt_f32_i32_e32 v100, v100
	v_mul_f32_e32 v95, 0xba000000, v100
	v_mul_f32_e32 v96, v131, v95
	v_mul_f32_e32 v97, 0x3fb8aa3b, v96
	v_fma_f32 v100, v96, s55, -v97
	v_rndne_f32_e32 v101, v97
	v_fmac_f32_e32 v100, 0x32a5705f, v96
	v_sub_f32_e32 v97, v97, v101
	v_add_f32_e32 v97, v97, v100
	v_exp_f32_e32 v97, v97
	v_cvt_i32_f32_e32 v101, v101
	v_cmp_ngt_f32_e32 vcc, s56, v96
	v_ldexp_f32 v97, v97, v101
	s_nop 0
	v_cndmask_b32_e32 v97, 0, v97, vcc
	v_cmp_nlt_f32_e32 vcc, s54, v96
	v_add_f32_e32 v52, v89, v52
	s_nop 0
	v_cndmask_b32_e32 v97, v242, v97, vcc
	v_mul_f32_e32 v52, v52, v97
	v_mul_f32_e32 v96, v132, v95
	v_mul_f32_e32 v97, 0x3fb8aa3b, v96
	v_fma_f32 v100, v96, s55, -v97
	v_rndne_f32_e32 v101, v97
	v_fmac_f32_e32 v100, 0x32a5705f, v96
	v_sub_f32_e32 v97, v97, v101
	v_add_f32_e32 v97, v97, v100
	v_exp_f32_e32 v97, v97
	v_cvt_i32_f32_e32 v101, v101
	v_cmp_ngt_f32_e32 vcc, s56, v96
	v_ldexp_f32 v97, v97, v101
	s_nop 0
	v_cndmask_b32_e32 v97, 0, v97, vcc
	v_cmp_nlt_f32_e32 vcc, s54, v96
	v_add_f32_e32 v53, v91, v53
	s_nop 0
	v_cndmask_b32_e32 v97, v242, v97, vcc
	v_mul_f32_e32 v53, v53, v97
	v_mul_f32_e32 v96, v133, v95
	v_mul_f32_e32 v97, 0x3fb8aa3b, v96
	v_fma_f32 v100, v96, s55, -v97
	v_rndne_f32_e32 v101, v97
	v_fmac_f32_e32 v100, 0x32a5705f, v96
	v_sub_f32_e32 v97, v97, v101
	v_add_f32_e32 v97, v97, v100
	v_exp_f32_e32 v97, v97
	v_cvt_i32_f32_e32 v101, v101
	v_cmp_ngt_f32_e32 vcc, s56, v96
	v_ldexp_f32 v97, v97, v101
	s_nop 0
	v_cndmask_b32_e32 v97, 0, v97, vcc
	v_cmp_nlt_f32_e32 vcc, s54, v96
	v_add_f32_e32 v54, v88, v54
	s_nop 0
	v_cndmask_b32_e32 v97, v242, v97, vcc
	v_mul_f32_e32 v54, v54, v97
	v_mul_f32_e32 v96, v134, v95
	v_mul_f32_e32 v97, 0x3fb8aa3b, v96
	v_fma_f32 v100, v96, s55, -v97
	v_rndne_f32_e32 v101, v97
	v_fmac_f32_e32 v100, 0x32a5705f, v96
	v_sub_f32_e32 v97, v97, v101
	v_add_f32_e32 v97, v97, v100
	v_exp_f32_e32 v97, v97
	v_cvt_i32_f32_e32 v101, v101
	v_cmp_ngt_f32_e32 vcc, s56, v96
	v_ldexp_f32 v97, v97, v101
	s_nop 0
	v_cndmask_b32_e32 v97, 0, v97, vcc
	v_cmp_nlt_f32_e32 vcc, s54, v96
	v_add_f32_e32 v55, v90, v55
	s_nop 0
	v_cndmask_b32_e32 v97, v242, v97, vcc
	v_mul_f32_e32 v55, v55, v97
	ds_write_b32 v98, v52 offset:39168
	ds_write_b32 v98, v53 offset:47360
	ds_write_b32 v99, v54 offset:6144
	ds_write_b32 v99, v55 offset:14336
	v_fmac_f32_e32 v65, v52, v52
	v_fmac_f32_e32 v65, v53, v53
	v_fmac_f32_e32 v64, v54, v54
	v_fmac_f32_e32 v64, v55, v55

; __device__ __forceinline__ int opaque_tid() { int t = threadIdx.x; asm volatile("" : "+v"(t)); return t; }
; __device__ __forceinline__ void moe_combine_item(const Params& p, int item) {
;   int tid = opaque_tid(), wave = tid >> 6, lane = tid & 63;
;   const u16* Y2 = (const u16*)(p.ws + O_Y2);
;   const int2* PPOS = (const int2*)(p.ws + O_ROUTE + R_PPOS);
;   const float2* TOKW = (const float2*)(p.ws + O_ROUTE + R_TOKW);
;   const float* MOD = (const float*)(p.ws + O_MOD);
; #pragma unroll
;   for (int i = 0; i < 4; i++) {
;     int row = item * 32 + wave * 4 + i;
;     int2 pp = PPOS[row]; float2 w = TOKW[row];
;     const float* gate = MOD + (size_t)(9 + (row >> 11)) * 6144 + 5120;
;     float* orow = p.out + (size_t)row * D;
; #pragma unroll
;     for (int q = 0; q < 4; q++) {
;       int cidx = q * 256 + lane * 4;
;       uint2 a = *(const uint2*)(Y2 + (size_t)pp.x * D + cidx);
;       uint2 b = *(const uint2*)(Y2 + (size_t)pp.y * D + cidx);
;       float4 gv = *(const float4*)(gate + cidx);
;       float4 o = *(const float4*)(orow + cidx);
;       o.x += gv.x * (w.x * __uint_as_float(a.x << 16) + w.y * __uint_as_float(b.x << 16));
;       o.y += gv.y * (w.x * __uint_as_float(a.x & 0xffff0000u) + w.y * __uint_as_float(b.x & 0xffff0000u));
;       o.z += gv.z * (w.x * __uint_as_float(a.y << 16) + w.y * __uint_as_float(b.y << 16));
;       o.w += gv.w * (w.x * __uint_as_float(a.y & 0xffff0000u) + w.y * __uint_as_float(b.y & 0xffff0000u));
;       *(float4*)(orow + cidx) = o;
;     }
.LBB0_1326:
	v_mov_b64_e32 v[6:7], s[50:51]
	global_load_dwordx4 v[8:11], v[6:7], off offset:336
	v_lshrrev_b32_e32 v1, 6, v228
	v_and_b32_e32 v2, 63, v228
	v_lshl_add_u32 v3, v1, 2, s4
	v_lshlrev_b32_e32 v28, 3, v2
	v_mov_b32_e32 v29, 0
	v_lshlrev_b32_e32 v30, 4, v2
	v_mov_b32_e32 v31, 0
	v_lshlrev_b32_e32 v4, 3, v3
	v_mov_b32_e32 v5, 0
	s_mov_b64 s[6:7], 0x6e12040
	s_mov_b64 s[10:11], 0x6dac000
	s_mov_b64 s[12:13], 0x6c05000
	s_waitcnt vmcnt(0)
	v_lshl_add_u64 v[80:81], v[8:9], 0, v[4:5]
	v_lshl_add_u64 v[82:83], v[80:81], 0, s[6:7]
	v_lshl_add_u64 v[84:85], v[80:81], 0, s[10:11]
	global_load_dwordx2 v[12:13], v[82:83], off
	global_load_dwordx2 v[14:15], v[84:85], off
	global_load_dwordx2 v[16:17], v[82:83], off offset:8
	global_load_dwordx2 v[18:19], v[84:85], off offset:8
	global_load_dwordx2 v[20:21], v[82:83], off offset:16
	global_load_dwordx2 v[22:23], v[84:85], off offset:16
	global_load_dwordx2 v[24:25], v[82:83], off offset:24
	global_load_dwordx2 v[26:27], v[84:85], off offset:24
	s_waitcnt vmcnt(6)
	v_ashrrev_i32_e32 v87, 31, v12
	v_mov_b32_e32 v86, v12
	v_lshlrev_b64 v[86:87], 11, v[86:87]
	v_lshl_add_u64 v[86:87], v[8:9], 0, v[86:87]
	v_lshl_add_u64 v[86:87], v[86:87], 0, v[28:29]
	v_ashrrev_i32_e32 v89, 31, v13
	v_mov_b32_e32 v88, v13
	v_lshlrev_b64 v[88:89], 11, v[88:89]
	v_lshl_add_u64 v[88:89], v[8:9], 0, v[88:89]
	v_lshl_add_u64 v[88:89], v[88:89], 0, v[28:29]
	v_mov_b32_e32 v90, v3
	v_ashrrev_i32_e32 v92, 11, v90
	v_add_u32_e32 v92, 9, v92
	v_mul_u32_u24_e32 v92, 0x6000, v92
	v_mov_b32_e32 v93, 0
	v_lshl_add_u64 v[92:93], v[8:9], 0, v[92:93]
	v_lshl_add_u64 v[92:93], v[92:93], 0, s[12:13]
	v_lshl_add_u64 v[92:93], v[92:93], 0, v[30:31]
	v_lshlrev_b32_e32 v94, 12, v90
	v_mov_b32_e32 v95, 0
	v_lshl_add_u64 v[94:95], v[10:11], 0, v[94:95]
	v_lshl_add_u64 v[94:95], v[94:95], 0, v[30:31]
	global_load_dwordx2 v[32:33], v[86:87], off
	global_load_dwordx2 v[40:41], v[88:89], off
	global_load_dwordx4 v[48:51], v[92:93], off
	global_load_dwordx4 v[64:67], v[94:95], off
	global_load_dwordx2 v[34:35], v[86:87], off offset:512
	global_load_dwordx2 v[42:43], v[88:89], off offset:512
	global_load_dwordx4 v[52:55], v[92:93], off offset:1024
	global_load_dwordx4 v[68:71], v[94:95], off offset:1024
	global_load_dwordx2 v[36:37], v[86:87], off offset:1024
	global_load_dwordx2 v[44:45], v[88:89], off offset:1024
	global_load_dwordx4 v[56:59], v[92:93], off offset:2048
	global_load_dwordx4 v[72:75], v[94:95], off offset:2048
	global_load_dwordx2 v[38:39], v[86:87], off offset:1536
	global_load_dwordx2 v[46:47], v[88:89], off offset:1536
	global_load_dwordx4 v[60:63], v[92:93], off offset:3072
	global_load_dwordx4 v[76:79], v[94:95], off offset:3072
	s_waitcnt vmcnt(12)
	v_lshlrev_b32_e32 v96, 16, v32
	v_and_b32_e32 v97, 0xffff0000, v40
	v_lshlrev_b32_e32 v98, 16, v40
	v_and_b32_e32 v99, 0xffff0000, v32
	v_pk_mul_f32 v[96:97], v[14:15], v[96:97]
	s_nop 0
	v_pk_fma_f32 v[98:99], v[14:15], v[98:99], v[96:97] op_sel:[1,0,0] op_sel_hi:[0,1,1]
	v_pk_fma_f32 v[64:65], v[48:49], v[98:99], v[64:65]
	v_lshlrev_b32_e32 v96, 16, v33
	v_and_b32_e32 v97, 0xffff0000, v41
	v_lshlrev_b32_e32 v98, 16, v41
	v_and_b32_e32 v99, 0xffff0000, v33
	v_pk_mul_f32 v[96:97], v[14:15], v[96:97]
	s_nop 0
	v_pk_fma_f32 v[98:99], v[14:15], v[98:99], v[96:97] op_sel:[1,0,0] op_sel_hi:[0,1,1]
	v_pk_fma_f32 v[66:67], v[50:51], v[98:99], v[66:67]
	global_store_dwordx4 v[94:95], v[64:67], off
	s_waitcnt vmcnt(9)
	v_lshlrev_b32_e32 v96, 16, v34
	v_and_b32_e32 v97, 0xffff0000, v42
	v_lshlrev_b32_e32 v98, 16, v42
	v_and_b32_e32 v99, 0xffff0000, v34
	v_pk_mul_f32 v[96:97], v[14:15], v[96:97]
	s_nop 0
	v_pk_fma_f32 v[98:99], v[14:15], v[98:99], v[96:97] op_sel:[1,0,0] op_sel_hi:[0,1,1]
	v_pk_fma_f32 v[68:69], v[52:53], v[98:99], v[68:69]
	v_lshlrev_b32_e32 v96, 16, v35
	v_and_b32_e32 v97, 0xffff0000, v43
	v_lshlrev_b32_e32 v98, 16, v43
	v_and_b32_e32 v99, 0xffff0000, v35
	v_pk_mul_f32 v[96:97], v[14:15], v[96:97]
	s_nop 0
	v_pk_fma_f32 v[98:99], v[14:15], v[98:99], v[96:97] op_sel:[1,0,0] op_sel_hi:[0,1,1]
	v_pk_fma_f32 v[70:71], v[54:55], v[98:99], v[70:71]
	global_store_dwordx4 v[94:95], v[68:71], off offset:1024
	s_waitcnt vmcnt(6)
	v_lshlrev_b32_e32 v96, 16, v36
	v_and_b32_e32 v97, 0xffff0000, v44
	v_lshlrev_b32_e32 v98, 16, v44
	v_and_b32_e32 v99, 0xffff0000, v36
	v_pk_mul_f32 v[96:97], v[14:15], v[96:97]
	s_nop 0
	v_pk_fma_f32 v[98:99], v[14:15], v[98:99], v[96:97] op_sel:[1,0,0] op_sel_hi:[0,1,1]
	v_pk_fma_f32 v[72:73], v[56:57], v[98:99], v[72:73]
	v_lshlrev_b32_e32 v96, 16, v37
	v_and_b32_e32 v97, 0xffff0000, v45
	v_lshlrev_b32_e32 v98, 16, v45
	v_and_b32_e32 v99, 0xffff0000, v37
	v_pk_mul_f32 v[96:97], v[14:15], v[96:97]
	s_nop 0
	v_pk_fma_f32 v[98:99], v[14:15], v[98:99], v[96:97] op_sel:[1,0,0] op_sel_hi:[0,1,1]
	v_pk_fma_f32 v[74:75], v[58:59], v[98:99], v[74:75]
	global_store_dwordx4 v[94:95], v[72:75], off offset:2048
	s_waitcnt vmcnt(3)
	v_lshlrev_b32_e32 v96, 16, v38
	v_and_b32_e32 v97, 0xffff0000, v46
	v_lshlrev_b32_e32 v98, 16, v46
	v_and_b32_e32 v99, 0xffff0000, v38
	v_pk_mul_f32 v[96:97], v[14:15], v[96:97]
	s_nop 0
	v_pk_fma_f32 v[98:99], v[14:15], v[98:99], v[96:97] op_sel:[1,0,0] op_sel_hi:[0,1,1]
	v_pk_fma_f32 v[76:77], v[60:61], v[98:99], v[76:77]
	v_lshlrev_b32_e32 v96, 16, v39
	v_and_b32_e32 v97, 0xffff0000, v47
	v_lshlrev_b32_e32 v98, 16, v47
	v_and_b32_e32 v99, 0xffff0000, v39
	v_pk_mul_f32 v[96:97], v[14:15], v[96:97]
	s_nop 0
	v_pk_fma_f32 v[98:99], v[14:15], v[98:99], v[96:97] op_sel:[1,0,0] op_sel_hi:[0,1,1]
	v_pk_fma_f32 v[78:79], v[62:63], v[98:99], v[78:79]
	global_store_dwordx4 v[94:95], v[76:79], off offset:3072
	s_waitcnt vmcnt(0)
; __device__ __forceinline__ void moe_combine_item(const Params& p, int item) {
;     ...
;     int2 pp = PPOS[row]; float2 w = TOKW[row];
;     const float* gate = MOD + (size_t)(9 + (row >> 11)) * 6144 + 5120;
;     float* orow = p.out + (size_t)row * D;
; #pragma unroll
;     for (int q = 0; q < 4; q++) {
;       int cidx = q * 256 + lane * 4;
;       uint2 a = *(const uint2*)(Y2 + (size_t)pp.x * D + cidx);
;       uint2 b = *(const uint2*)(Y2 + (size_t)pp.y * D + cidx);
;       float4 gv = *(const float4*)(gate + cidx);
;       float4 o = *(const float4*)(orow + cidx);
;       o.x += gv.x * (w.x * __uint_as_float(a.x << 16) + w.y * __uint_as_float(b.x << 16));
;       o.y += gv.y * (w.x * __uint_as_float(a.x & 0xffff0000u) + w.y * __uint_as_float(b.x & 0xffff0000u));
;       o.z += gv.z * (w.x * __uint_as_float(a.y << 16) + w.y * __uint_as_float(b.y << 16));
;       o.w += gv.w * (w.x * __uint_as_float(a.y & 0xffff0000u) + w.y * __uint_as_float(b.y & 0xffff0000u));
;       *(float4*)(orow + cidx) = o;
	v_ashrrev_i32_e32 v87, 31, v16
	v_mov_b32_e32 v86, v16
	v_lshlrev_b64 v[86:87], 11, v[86:87]
	v_lshl_add_u64 v[86:87], v[8:9], 0, v[86:87]
	v_lshl_add_u64 v[86:87], v[86:87], 0, v[28:29]
	v_ashrrev_i32_e32 v89, 31, v17
	v_mov_b32_e32 v88, v17
	v_lshlrev_b64 v[88:89], 11, v[88:89]
	v_lshl_add_u64 v[88:89], v[8:9], 0, v[88:89]
	v_lshl_add_u64 v[88:89], v[88:89], 0, v[28:29]
	v_add_u32_e32 v90, 1, v3
	v_ashrrev_i32_e32 v92, 11, v90
	v_add_u32_e32 v92, 9, v92
	v_mul_u32_u24_e32 v92, 0x6000, v92
	v_mov_b32_e32 v93, 0
	v_lshl_add_u64 v[92:93], v[8:9], 0, v[92:93]
	v_lshl_add_u64 v[92:93], v[92:93], 0, s[12:13]
	v_lshl_add_u64 v[92:93], v[92:93], 0, v[30:31]
	v_lshlrev_b32_e32 v94, 12, v90
	v_mov_b32_e32 v95, 0
	v_lshl_add_u64 v[94:95], v[10:11], 0, v[94:95]
	v_lshl_add_u64 v[94:95], v[94:95], 0, v[30:31]
	global_load_dwordx2 v[32:33], v[86:87], off
	global_load_dwordx2 v[40:41], v[88:89], off
	global_load_dwordx4 v[48:51], v[92:93], off
	global_load_dwordx4 v[64:67], v[94:95], off
	global_load_dwordx2 v[34:35], v[86:87], off offset:512
	global_load_dwordx2 v[42:43], v[88:89], off offset:512
	global_load_dwordx4 v[52:55], v[92:93], off offset:1024
	global_load_dwordx4 v[68:71], v[94:95], off offset:1024
	global_load_dwordx2 v[36:37], v[86:87], off offset:1024
	global_load_dwordx2 v[44:45], v[88:89], off offset:1024
	global_load_dwordx4 v[56:59], v[92:93], off offset:2048
	global_load_dwordx4 v[72:75], v[94:95], off offset:2048
	global_load_dwordx2 v[38:39], v[86:87], off offset:1536
	global_load_dwordx2 v[46:47], v[88:89], off offset:1536
	global_load_dwordx4 v[60:63], v[92:93], off offset:3072
	global_load_dwordx4 v[76:79], v[94:95], off offset:3072
	s_waitcnt vmcnt(12)
	v_lshlrev_b32_e32 v96, 16, v32
	v_and_b32_e32 v97, 0xffff0000, v40
	v_lshlrev_b32_e32 v98, 16, v40
	v_and_b32_e32 v99, 0xffff0000, v32
	v_pk_mul_f32 v[96:97], v[18:19], v[96:97]
	s_nop 0
	v_pk_fma_f32 v[98:99], v[18:19], v[98:99], v[96:97] op_sel:[1,0,0] op_sel_hi:[0,1,1]
	v_pk_fma_f32 v[64:65], v[48:49], v[98:99], v[64:65]
	v_lshlrev_b32_e32 v96, 16, v33
	v_and_b32_e32 v97, 0xffff0000, v41
	v_lshlrev_b32_e32 v98, 16, v41
	v_and_b32_e32 v99, 0xffff0000, v33
	v_pk_mul_f32 v[96:97], v[18:19], v[96:97]
	s_nop 0
	v_pk_fma_f32 v[98:99], v[18:19], v[98:99], v[96:97] op_sel:[1,0,0] op_sel_hi:[0,1,1]
	v_pk_fma_f32 v[66:67], v[50:51], v[98:99], v[66:67]
	global_store_dwordx4 v[94:95], v[64:67], off
	s_waitcnt vmcnt(9)
	v_lshlrev_b32_e32 v96, 16, v34
	v_and_b32_e32 v97, 0xffff0000, v42
	v_lshlrev_b32_e32 v98, 16, v42
	v_and_b32_e32 v99, 0xffff0000, v34
	v_pk_mul_f32 v[96:97], v[18:19], v[96:97]
	s_nop 0
	v_pk_fma_f32 v[98:99], v[18:19], v[98:99], v[96:97] op_sel:[1,0,0] op_sel_hi:[0,1,1]
	v_pk_fma_f32 v[68:69], v[52:53], v[98:99], v[68:69]
	v_lshlrev_b32_e32 v96, 16, v35
	v_and_b32_e32 v97, 0xffff0000, v43
	v_lshlrev_b32_e32 v98, 16, v43
	v_and_b32_e32 v99, 0xffff0000, v35
	v_pk_mul_f32 v[96:97], v[18:19], v[96:97]
	s_nop 0
	v_pk_fma_f32 v[98:99], v[18:19], v[98:99], v[96:97] op_sel:[1,0,0] op_sel_hi:[0,1,1]
	v_pk_fma_f32 v[70:71], v[54:55], v[98:99], v[70:71]
	global_store_dwordx4 v[94:95], v[68:71], off offset:1024
	s_waitcnt vmcnt(6)
	v_lshlrev_b32_e32 v96, 16, v36
	v_and_b32_e32 v97, 0xffff0000, v44
	v_lshlrev_b32_e32 v98, 16, v44
	v_and_b32_e32 v99, 0xffff0000, v36
	v_pk_mul_f32 v[96:97], v[18:19], v[96:97]
	s_nop 0
	v_pk_fma_f32 v[98:99], v[18:19], v[98:99], v[96:97] op_sel:[1,0,0] op_sel_hi:[0,1,1]
	v_pk_fma_f32 v[72:73], v[56:57], v[98:99], v[72:73]
	v_lshlrev_b32_e32 v96, 16, v37
	v_and_b32_e32 v97, 0xffff0000, v45
	v_lshlrev_b32_e32 v98, 16, v45
	v_and_b32_e32 v99, 0xffff0000, v37
	v_pk_mul_f32 v[96:97], v[18:19], v[96:97]
	s_nop 0
	v_pk_fma_f32 v[98:99], v[18:19], v[98:99], v[96:97] op_sel:[1,0,0] op_sel_hi:[0,1,1]
	v_pk_fma_f32 v[74:75], v[58:59], v[98:99], v[74:75]
	global_store_dwordx4 v[94:95], v[72:75], off offset:2048
	s_waitcnt vmcnt(3)
	v_lshlrev_b32_e32 v96, 16, v38
	v_and_b32_e32 v97, 0xffff0000, v46
	v_lshlrev_b32_e32 v98, 16, v46
	v_and_b32_e32 v99, 0xffff0000, v38
	v_pk_mul_f32 v[96:97], v[18:19], v[96:97]
	s_nop 0
	v_pk_fma_f32 v[98:99], v[18:19], v[98:99], v[96:97] op_sel:[1,0,0] op_sel_hi:[0,1,1]
	v_pk_fma_f32 v[76:77], v[60:61], v[98:99], v[76:77]
	v_lshlrev_b32_e32 v96, 16, v39
	v_and_b32_e32 v97, 0xffff0000, v47
	v_lshlrev_b32_e32 v98, 16, v47
	v_and_b32_e32 v99, 0xffff0000, v39
	v_pk_mul_f32 v[96:97], v[18:19], v[96:97]
	s_nop 0
	v_pk_fma_f32 v[98:99], v[18:19], v[98:99], v[96:97] op_sel:[1,0,0] op_sel_hi:[0,1,1]
	v_pk_fma_f32 v[78:79], v[62:63], v[98:99], v[78:79]
	global_store_dwordx4 v[94:95], v[76:79], off offset:3072
	s_waitcnt vmcnt(0)
	v_ashrrev_i32_e32 v87, 31, v20
	v_mov_b32_e32 v86, v20
	v_lshlrev_b64 v[86:87], 11, v[86:87]
	v_lshl_add_u64 v[86:87], v[8:9], 0, v[86:87]
	v_lshl_add_u64 v[86:87], v[86:87], 0, v[28:29]
	v_ashrrev_i32_e32 v89, 31, v21
	v_mov_b32_e32 v88, v21
	v_lshlrev_b64 v[88:89], 11, v[88:89]
	v_lshl_add_u64 v[88:89], v[8:9], 0, v[88:89]
	v_lshl_add_u64 v[88:89], v[88:89], 0, v[28:29]
	v_add_u32_e32 v90, 2, v3
	v_ashrrev_i32_e32 v92, 11, v90
	v_add_u32_e32 v92, 9, v92
	v_mul_u32_u24_e32 v92, 0x6000, v92
	v_mov_b32_e32 v93, 0
	v_lshl_add_u64 v[92:93], v[8:9], 0, v[92:93]
	v_lshl_add_u64 v[92:93], v[92:93], 0, s[12:13]
	v_lshl_add_u64 v[92:93], v[92:93], 0, v[30:31]
	v_lshlrev_b32_e32 v94, 12, v90
	v_mov_b32_e32 v95, 0
	v_lshl_add_u64 v[94:95], v[10:11], 0, v[94:95]
	v_lshl_add_u64 v[94:95], v[94:95], 0, v[30:31]
	global_load_dwordx2 v[32:33], v[86:87], off
	global_load_dwordx2 v[40:41], v[88:89], off
	global_load_dwordx4 v[48:51], v[92:93], off
	global_load_dwordx4 v[64:67], v[94:95], off
	global_load_dwordx2 v[34:35], v[86:87], off offset:512
	global_load_dwordx2 v[42:43], v[88:89], off offset:512
	global_load_dwordx4 v[52:55], v[92:93], off offset:1024
	global_load_dwordx4 v[68:71], v[94:95], off offset:1024
	global_load_dwordx2 v[36:37], v[86:87], off offset:1024
	global_load_dwordx2 v[44:45], v[88:89], off offset:1024
	global_load_dwordx4 v[56:59], v[92:93], off offset:2048
	global_load_dwordx4 v[72:75], v[94:95], off offset:2048
	global_load_dwordx2 v[38:39], v[86:87], off offset:1536
	global_load_dwordx2 v[46:47], v[88:89], off offset:1536
	global_load_dwordx4 v[60:63], v[92:93], off offset:3072
	global_load_dwordx4 v[76:79], v[94:95], off offset:3072
	s_waitcnt vmcnt(12)
; __device__ __forceinline__ void moe_combine_item(const Params& p, int item) {
;     ...
;     int2 pp = PPOS[row]; float2 w = TOKW[row];
;     const float* gate = MOD + (size_t)(9 + (row >> 11)) * 6144 + 5120;
;     float* orow = p.out + (size_t)row * D;
; #pragma unroll
;     for (int q = 0; q < 4; q++) {
;       int cidx = q * 256 + lane * 4;
;       uint2 a = *(const uint2*)(Y2 + (size_t)pp.x * D + cidx);
;       uint2 b = *(const uint2*)(Y2 + (size_t)pp.y * D + cidx);
;       float4 gv = *(const float4*)(gate + cidx);
;       float4 o = *(const float4*)(orow + cidx);
;       o.x += gv.x * (w.x * __uint_as_float(a.x << 16) + w.y * __uint_as_float(b.x << 16));
;       o.y += gv.y * (w.x * __uint_as_float(a.x & 0xffff0000u) + w.y * __uint_as_float(b.x & 0xffff0000u));
;       o.z += gv.z * (w.x * __uint_as_float(a.y << 16) + w.y * __uint_as_float(b.y << 16));
;       o.w += gv.w * (w.x * __uint_as_float(a.y & 0xffff0000u) + w.y * __uint_as_float(b.y & 0xffff0000u));
;       *(float4*)(orow + cidx) = o;
	v_lshlrev_b32_e32 v96, 16, v32
	v_and_b32_e32 v97, 0xffff0000, v40
	v_lshlrev_b32_e32 v98, 16, v40
	v_and_b32_e32 v99, 0xffff0000, v32
	v_pk_mul_f32 v[96:97], v[22:23], v[96:97]
	s_nop 0
	v_pk_fma_f32 v[98:99], v[22:23], v[98:99], v[96:97] op_sel:[1,0,0] op_sel_hi:[0,1,1]
	v_pk_fma_f32 v[64:65], v[48:49], v[98:99], v[64:65]
	v_lshlrev_b32_e32 v96, 16, v33
	v_and_b32_e32 v97, 0xffff0000, v41
	v_lshlrev_b32_e32 v98, 16, v41
	v_and_b32_e32 v99, 0xffff0000, v33
	v_pk_mul_f32 v[96:97], v[22:23], v[96:97]
	s_nop 0
	v_pk_fma_f32 v[98:99], v[22:23], v[98:99], v[96:97] op_sel:[1,0,0] op_sel_hi:[0,1,1]
	v_pk_fma_f32 v[66:67], v[50:51], v[98:99], v[66:67]
	global_store_dwordx4 v[94:95], v[64:67], off
	s_waitcnt vmcnt(9)
	v_lshlrev_b32_e32 v96, 16, v34
	v_and_b32_e32 v97, 0xffff0000, v42
	v_lshlrev_b32_e32 v98, 16, v42
	v_and_b32_e32 v99, 0xffff0000, v34
	v_pk_mul_f32 v[96:97], v[22:23], v[96:97]
	s_nop 0
	v_pk_fma_f32 v[98:99], v[22:23], v[98:99], v[96:97] op_sel:[1,0,0] op_sel_hi:[0,1,1]
	v_pk_fma_f32 v[68:69], v[52:53], v[98:99], v[68:69]
	v_lshlrev_b32_e32 v96, 16, v35
	v_and_b32_e32 v97, 0xffff0000, v43
	v_lshlrev_b32_e32 v98, 16, v43
	v_and_b32_e32 v99, 0xffff0000, v35
	v_pk_mul_f32 v[96:97], v[22:23], v[96:97]
	s_nop 0
	v_pk_fma_f32 v[98:99], v[22:23], v[98:99], v[96:97] op_sel:[1,0,0] op_sel_hi:[0,1,1]
	v_pk_fma_f32 v[70:71], v[54:55], v[98:99], v[70:71]
	global_store_dwordx4 v[94:95], v[68:71], off offset:1024
	s_waitcnt vmcnt(6)
	v_lshlrev_b32_e32 v96, 16, v36
	v_and_b32_e32 v97, 0xffff0000, v44
	v_lshlrev_b32_e32 v98, 16, v44
	v_and_b32_e32 v99, 0xffff0000, v36
	v_pk_mul_f32 v[96:97], v[22:23], v[96:97]
	s_nop 0
	v_pk_fma_f32 v[98:99], v[22:23], v[98:99], v[96:97] op_sel:[1,0,0] op_sel_hi:[0,1,1]
	v_pk_fma_f32 v[72:73], v[56:57], v[98:99], v[72:73]
	v_lshlrev_b32_e32 v96, 16, v37
	v_and_b32_e32 v97, 0xffff0000, v45
	v_lshlrev_b32_e32 v98, 16, v45
	v_and_b32_e32 v99, 0xffff0000, v37
	v_pk_mul_f32 v[96:97], v[22:23], v[96:97]
	s_nop 0
	v_pk_fma_f32 v[98:99], v[22:23], v[98:99], v[96:97] op_sel:[1,0,0] op_sel_hi:[0,1,1]
	v_pk_fma_f32 v[74:75], v[58:59], v[98:99], v[74:75]
	global_store_dwordx4 v[94:95], v[72:75], off offset:2048
	s_waitcnt vmcnt(3)
	v_lshlrev_b32_e32 v96, 16, v38
	v_and_b32_e32 v97, 0xffff0000, v46
	v_lshlrev_b32_e32 v98, 16, v46
	v_and_b32_e32 v99, 0xffff0000, v38
	v_pk_mul_f32 v[96:97], v[22:23], v[96:97]
	s_nop 0
	v_pk_fma_f32 v[98:99], v[22:23], v[98:99], v[96:97] op_sel:[1,0,0] op_sel_hi:[0,1,1]
	v_pk_fma_f32 v[76:77], v[60:61], v[98:99], v[76:77]
	v_lshlrev_b32_e32 v96, 16, v39
	v_and_b32_e32 v97, 0xffff0000, v47
	v_lshlrev_b32_e32 v98, 16, v47
	v_and_b32_e32 v99, 0xffff0000, v39
	v_pk_mul_f32 v[96:97], v[22:23], v[96:97]
	s_nop 0
	v_pk_fma_f32 v[98:99], v[22:23], v[98:99], v[96:97] op_sel:[1,0,0] op_sel_hi:[0,1,1]
	v_pk_fma_f32 v[78:79], v[62:63], v[98:99], v[78:79]
	global_store_dwordx4 v[94:95], v[76:79], off offset:3072
	s_waitcnt vmcnt(0)
	v_ashrrev_i32_e32 v87, 31, v24
	v_mov_b32_e32 v86, v24
	v_lshlrev_b64 v[86:87], 11, v[86:87]
	v_lshl_add_u64 v[86:87], v[8:9], 0, v[86:87]
	v_lshl_add_u64 v[86:87], v[86:87], 0, v[28:29]
	v_ashrrev_i32_e32 v89, 31, v25
	v_mov_b32_e32 v88, v25
	v_lshlrev_b64 v[88:89], 11, v[88:89]
	v_lshl_add_u64 v[88:89], v[8:9], 0, v[88:89]
	v_lshl_add_u64 v[88:89], v[88:89], 0, v[28:29]
	v_add_u32_e32 v90, 3, v3
	v_ashrrev_i32_e32 v92, 11, v90
	v_add_u32_e32 v92, 9, v92
	v_mul_u32_u24_e32 v92, 0x6000, v92
	v_mov_b32_e32 v93, 0
	v_lshl_add_u64 v[92:93], v[8:9], 0, v[92:93]
	v_lshl_add_u64 v[92:93], v[92:93], 0, s[12:13]
	v_lshl_add_u64 v[92:93], v[92:93], 0, v[30:31]
	v_lshlrev_b32_e32 v94, 12, v90
	v_mov_b32_e32 v95, 0
	v_lshl_add_u64 v[94:95], v[10:11], 0, v[94:95]
	v_lshl_add_u64 v[94:95], v[94:95], 0, v[30:31]
	global_load_dwordx2 v[32:33], v[86:87], off
	global_load_dwordx2 v[40:41], v[88:89], off
	global_load_dwordx4 v[48:51], v[92:93], off
	global_load_dwordx4 v[64:67], v[94:95], off
	global_load_dwordx2 v[34:35], v[86:87], off offset:512
	global_load_dwordx2 v[42:43], v[88:89], off offset:512
	global_load_dwordx4 v[52:55], v[92:93], off offset:1024
	global_load_dwordx4 v[68:71], v[94:95], off offset:1024
	global_load_dwordx2 v[36:37], v[86:87], off offset:1024
	global_load_dwordx2 v[44:45], v[88:89], off offset:1024
	global_load_dwordx4 v[56:59], v[92:93], off offset:2048
	global_load_dwordx4 v[72:75], v[94:95], off offset:2048
	global_load_dwordx2 v[38:39], v[86:87], off offset:1536
	global_load_dwordx2 v[46:47], v[88:89], off offset:1536
	global_load_dwordx4 v[60:63], v[92:93], off offset:3072
	global_load_dwordx4 v[76:79], v[94:95], off offset:3072
	s_waitcnt vmcnt(12)
; #define PP (*get_params())
; #define PH(k) for (int rep_ = 0; rep_ < (((DBLMASK >> (k)) & 1) ? 2 : 1); ++rep_) if (ONLY < 0 || ONLY == (k))
; #define GRID_LOOP(it, n) for (int it = blockIdx.x; it < (n); it += gridDim.x)
; __device__ __forceinline__ void moe_combine_item(const Params& p, int item) {
;     ...
;     for (int q = 0; q < 4; q++) {
;       int cidx = q * 256 + lane * 4;
;       uint2 a = *(const uint2*)(Y2 + (size_t)pp.x * D + cidx);
;       uint2 b = *(const uint2*)(Y2 + (size_t)pp.y * D + cidx);
;       float4 gv = *(const float4*)(gate + cidx);
;       float4 o = *(const float4*)(orow + cidx);
;       o.x += gv.x * (w.x * __uint_as_float(a.x << 16) + w.y * __uint_as_float(b.x << 16));
;       o.y += gv.y * (w.x * __uint_as_float(a.x & 0xffff0000u) + w.y * __uint_as_float(b.x & 0xffff0000u));
;       o.z += gv.z * (w.x * __uint_as_float(a.y << 16) + w.y * __uint_as_float(b.y << 16));
;       o.w += gv.w * (w.x * __uint_as_float(a.y & 0xffff0000u) + w.y * __uint_as_float(b.y & 0xffff0000u));
;       *(float4*)(orow + cidx) = o;
;     }
; __global__ void __launch_bounds__(512, 2) fwd_megakernel(Params p) {
;     ...
;       PH(26) GRID_LOOP(it, TL / 32) moe_combine_item(PP, it);
	v_lshlrev_b32_e32 v96, 16, v32
	v_and_b32_e32 v97, 0xffff0000, v40
	v_lshlrev_b32_e32 v98, 16, v40
	v_and_b32_e32 v99, 0xffff0000, v32
	v_pk_mul_f32 v[96:97], v[26:27], v[96:97]
	s_nop 0
	v_pk_fma_f32 v[98:99], v[26:27], v[98:99], v[96:97] op_sel:[1,0,0] op_sel_hi:[0,1,1]
	v_pk_fma_f32 v[64:65], v[48:49], v[98:99], v[64:65]
	v_lshlrev_b32_e32 v96, 16, v33
	v_and_b32_e32 v97, 0xffff0000, v41
	v_lshlrev_b32_e32 v98, 16, v41
	v_and_b32_e32 v99, 0xffff0000, v33
	v_pk_mul_f32 v[96:97], v[26:27], v[96:97]
	s_nop 0
	v_pk_fma_f32 v[98:99], v[26:27], v[98:99], v[96:97] op_sel:[1,0,0] op_sel_hi:[0,1,1]
	v_pk_fma_f32 v[66:67], v[50:51], v[98:99], v[66:67]
	global_store_dwordx4 v[94:95], v[64:67], off
	s_waitcnt vmcnt(9)
	v_lshlrev_b32_e32 v96, 16, v34
	v_and_b32_e32 v97, 0xffff0000, v42
	v_lshlrev_b32_e32 v98, 16, v42
	v_and_b32_e32 v99, 0xffff0000, v34
	v_pk_mul_f32 v[96:97], v[26:27], v[96:97]
	s_nop 0
	v_pk_fma_f32 v[98:99], v[26:27], v[98:99], v[96:97] op_sel:[1,0,0] op_sel_hi:[0,1,1]
	v_pk_fma_f32 v[68:69], v[52:53], v[98:99], v[68:69]
	v_lshlrev_b32_e32 v96, 16, v35
	v_and_b32_e32 v97, 0xffff0000, v43
	v_lshlrev_b32_e32 v98, 16, v43
	v_and_b32_e32 v99, 0xffff0000, v35
	v_pk_mul_f32 v[96:97], v[26:27], v[96:97]
	s_nop 0
	v_pk_fma_f32 v[98:99], v[26:27], v[98:99], v[96:97] op_sel:[1,0,0] op_sel_hi:[0,1,1]
	v_pk_fma_f32 v[70:71], v[54:55], v[98:99], v[70:71]
	global_store_dwordx4 v[94:95], v[68:71], off offset:1024
	s_waitcnt vmcnt(6)
	v_lshlrev_b32_e32 v96, 16, v36
	v_and_b32_e32 v97, 0xffff0000, v44
	v_lshlrev_b32_e32 v98, 16, v44
	v_and_b32_e32 v99, 0xffff0000, v36
	v_pk_mul_f32 v[96:97], v[26:27], v[96:97]
	s_nop 0
	v_pk_fma_f32 v[98:99], v[26:27], v[98:99], v[96:97] op_sel:[1,0,0] op_sel_hi:[0,1,1]
	v_pk_fma_f32 v[72:73], v[56:57], v[98:99], v[72:73]
	v_lshlrev_b32_e32 v96, 16, v37
	v_and_b32_e32 v97, 0xffff0000, v45
	v_lshlrev_b32_e32 v98, 16, v45
	v_and_b32_e32 v99, 0xffff0000, v37
	v_pk_mul_f32 v[96:97], v[26:27], v[96:97]
	s_nop 0
	v_pk_fma_f32 v[98:99], v[26:27], v[98:99], v[96:97] op_sel:[1,0,0] op_sel_hi:[0,1,1]
	v_pk_fma_f32 v[74:75], v[58:59], v[98:99], v[74:75]
	global_store_dwordx4 v[94:95], v[72:75], off offset:2048
	s_waitcnt vmcnt(3)
	v_lshlrev_b32_e32 v96, 16, v38
	v_and_b32_e32 v97, 0xffff0000, v46
	v_lshlrev_b32_e32 v98, 16, v46
	v_and_b32_e32 v99, 0xffff0000, v38
	v_pk_mul_f32 v[96:97], v[26:27], v[96:97]
	s_nop 0
	v_pk_fma_f32 v[98:99], v[26:27], v[98:99], v[96:97] op_sel:[1,0,0] op_sel_hi:[0,1,1]
	v_pk_fma_f32 v[76:77], v[60:61], v[98:99], v[76:77]
	v_lshlrev_b32_e32 v96, 16, v39
	v_and_b32_e32 v97, 0xffff0000, v47
	v_lshlrev_b32_e32 v98, 16, v47
	v_and_b32_e32 v99, 0xffff0000, v39
	v_pk_mul_f32 v[96:97], v[26:27], v[96:97]
	s_nop 0
	v_pk_fma_f32 v[98:99], v[26:27], v[98:99], v[96:97] op_sel:[1,0,0] op_sel_hi:[0,1,1]
	v_pk_fma_f32 v[78:79], v[62:63], v[98:99], v[78:79]
	global_store_dwordx4 v[94:95], v[76:79], off offset:3072
	s_add_i32 s5, s5, s8
	s_add_i32 s4, s4, s9
	s_cmpk_lt_i32 s5, 0x200
	s_cbranch_scc1 .LBB0_1326
